# swiglu epilogue rewritten by hand: ssq loads hoisted, rstd batched, no per-row vmcnt(0); loop-head vmcnt(0) removed
# speedup vs baseline: 1.0196x; 1.0196x over previous
; #define PG8_STAGE(bufoff, gbase, voff) do { _Pragma("unroll") for (int _i = 0; _i < 2; ++_i) \
;         __builtin_amdgcn_global_load_lds((const unsigned*)((const char*)(gbase) + (voff)[_i]), (PG8_LAS unsigned*)(lds + (bufoff) + ldsw + _i * 8192), 16, 0, 0); } while (0)
; #define PG8_LDA(dst, b, h) do { _Pragma("unroll") for (int m = 0; m < 4; ++m) _Pragma("unroll") for (int k = 0; k < 2; ++k) dst[m][k] = *(const PG8_LAS bf16x8*)(lds + PG8_SA(b, h) + aoff + m * 2048 + k * 1024); } while (0)
; #define PG8_LDB(dst, b, h) do { _Pragma("unroll") for (int n = 0; n < 2; ++n) _Pragma("unroll") for (int k = 0; k < 2; ++k) dst[n][k] = *(const PG8_LAS bf16x8*)(lds + PG8_SB(b, h) + boff + n * 2048 + k * 1024); } while (0)
; #define PG8_MMA(ai, bj, At, Bt) do { __builtin_amdgcn_s_setprio(1); _Pragma("unroll") for (int m = 0; m < 4; ++m) _Pragma("unroll") for (int n = 0; n < 2; ++n) _Pragma("unroll") for (int k = 0; k < 2; ++k) \
;         acc[ai][bj][m][n] = __builtin_amdgcn_mfma_f32_16x16x32_bf16(Bt[n][k], At[m][k], acc[ai][bj][m][n], 0, 0, 0); __builtin_amdgcn_s_setprio(0); } while (0)
; #define PG8_WAIT_V(n) asm volatile("s_waitcnt vmcnt(" #n ")" ::: "memory")
; #define PG8_WAIT_L(n) asm volatile("s_waitcnt lgkmcnt(" #n ")" ::: "memory")
; #define PG8_BAR __builtin_amdgcn_s_barrier()
; #define PG8_SCHED __builtin_amdgcn_sched_barrier(0)
; template <class Epi, class Sched, bool ALIGN_EPI = false, bool SP2 = false>
; __device__ __forceinline__ void gemm_phase(PG8_LAS unsigned char* lds, const Gemm g, const Sched& S, const Epi& E) {
;     ...
;             PG8_LDB(B0, 0, 0); PG8_LDB(B1, 0, 1); PG8_SCHED; PG8_LDA(At, 0, 0); PG8_STAGE(PG8_SA(1, 1), a1 + hstepA, voffA);
;             PG8_WAIT_V(8); PG8_WAIT_L(0); PG8_BAR; PG8_MMA(0, 0, At, B0); PG8_MMA(0, 1, At, B1); PG8_BAR; PG8_SCHED;
;     ...
; #pragma unroll
;         for (int a = 0; a < 2; ++a)
; #pragma unroll
;             for (int b = 0; b < 2; ++b)
; #pragma unroll
;                 for (int m = 0; m < 4; ++m)
; #pragma unroll
;                     for (int n = 0; n < 2; ++n) acc[a][b][m][n] = (f32x4){0.f, 0.f, 0.f, 0.f};
;         cur = nxt; cA = nA; cB = nB; ++ui;
.LBB0_735:
	s_ashr_i32 s19, s18, 31
	s_lshl_b64 s[4:5], s[18:19], 20
	s_add_u32 s20, s0, s4
	s_addc_u32 s21, s1, s5
	s_and_b64 s[4:5], s[8:9], exec
	s_cselect_b32 s19, s21, s29
	s_cselect_b32 s56, s20, s28
	s_ashr_i32 s17, s16, 31
	s_lshl_b64 s[4:5], s[16:17], 20
	s_add_u32 s22, s3, s4
	s_addc_u32 s23, s24, s5
	s_and_b64 s[4:5], s[8:9], exec
	s_cselect_b32 s17, s23, s31
	s_cselect_b32 s57, s22, s30
	s_add_u32 s28, s28, 0x80080
	s_addc_u32 s29, s29, 0
	s_add_u32 s58, s30, 0x100
	v_mov_b32_e32 v0, 0
	s_addc_u32 s59, s31, 0
	s_mov_b32 s60, -2
	v_mov_b32_e32 v1, v0
	v_mov_b32_e32 v2, v0
	v_mov_b32_e32 v3, v0
	v_mov_b32_e32 v12, v0
	v_mov_b32_e32 v13, v0
	v_mov_b32_e32 v14, v0
	v_mov_b32_e32 v15, v0
	v_mov_b32_e32 v24, v0
	v_mov_b32_e32 v25, v0
	v_mov_b32_e32 v26, v0
	v_mov_b32_e32 v27, v0
	v_mov_b32_e32 v28, v0
	v_mov_b32_e32 v29, v0
	v_mov_b32_e32 v30, v0
	v_mov_b32_e32 v31, v0
	v_mov_b32_e32 v40, v0
	v_mov_b32_e32 v41, v0
	v_mov_b32_e32 v42, v0
	v_mov_b32_e32 v43, v0
	v_mov_b32_e32 v44, v0
	v_mov_b32_e32 v45, v0
	v_mov_b32_e32 v46, v0
	v_mov_b32_e32 v47, v0
	v_mov_b32_e32 v56, v0
	v_mov_b32_e32 v57, v0
	v_mov_b32_e32 v58, v0
	v_mov_b32_e32 v59, v0
	v_mov_b32_e32 v60, v0
	v_mov_b32_e32 v61, v0
	v_mov_b32_e32 v62, v0
	v_mov_b32_e32 v63, v0
	v_mov_b32_e32 v4, v0
	v_mov_b32_e32 v5, v0
	v_mov_b32_e32 v6, v0
	v_mov_b32_e32 v7, v0
	v_mov_b32_e32 v8, v0
	v_mov_b32_e32 v9, v0
	v_mov_b32_e32 v10, v0
	v_mov_b32_e32 v11, v0
	v_mov_b32_e32 v16, v0
	v_mov_b32_e32 v17, v0
	v_mov_b32_e32 v18, v0
	v_mov_b32_e32 v19, v0
	v_mov_b32_e32 v20, v0
	v_mov_b32_e32 v21, v0
	v_mov_b32_e32 v22, v0
	v_mov_b32_e32 v23, v0
	v_mov_b32_e32 v32, v0
	v_mov_b32_e32 v33, v0
	v_mov_b32_e32 v34, v0
	v_mov_b32_e32 v35, v0
	v_mov_b32_e32 v36, v0
	v_mov_b32_e32 v37, v0
	v_mov_b32_e32 v38, v0
	v_mov_b32_e32 v39, v0
	v_mov_b32_e32 v48, v0
	v_mov_b32_e32 v49, v0
	v_mov_b32_e32 v50, v0
	v_mov_b32_e32 v51, v0
	v_mov_b32_e32 v52, v0
	v_mov_b32_e32 v53, v0
	v_mov_b32_e32 v54, v0
	v_mov_b32_e32 v55, v0
	v_mov_b32_e32 v72, v0
	v_mov_b32_e32 v73, v0
	v_mov_b32_e32 v74, v0
	v_mov_b32_e32 v75, v0
	v_mov_b32_e32 v76, v0
	v_mov_b32_e32 v77, v0
	v_mov_b32_e32 v78, v0
	v_mov_b32_e32 v79, v0
	v_mov_b32_e32 v88, v0
	v_mov_b32_e32 v89, v0
	v_mov_b32_e32 v90, v0
	v_mov_b32_e32 v91, v0
	v_mov_b32_e32 v92, v0
	v_mov_b32_e32 v93, v0
	v_mov_b32_e32 v94, v0
	v_mov_b32_e32 v95, v0
	v_mov_b32_e32 v104, v0
	v_mov_b32_e32 v105, v0
	v_mov_b32_e32 v106, v0
	v_mov_b32_e32 v107, v0
	v_mov_b32_e32 v108, v0
	v_mov_b32_e32 v109, v0
	v_mov_b32_e32 v110, v0
	v_mov_b32_e32 v111, v0
	v_mov_b32_e32 v120, v0
	v_mov_b32_e32 v121, v0
	v_mov_b32_e32 v122, v0
	v_mov_b32_e32 v123, v0
	v_mov_b32_e32 v124, v0
	v_mov_b32_e32 v125, v0
	v_mov_b32_e32 v126, v0
	v_mov_b32_e32 v127, v0
	v_mov_b32_e32 v64, v0
	v_mov_b32_e32 v65, v0
	v_mov_b32_e32 v66, v0
	v_mov_b32_e32 v67, v0
	v_mov_b32_e32 v68, v0
	v_mov_b32_e32 v69, v0
	v_mov_b32_e32 v70, v0
	v_mov_b32_e32 v71, v0
	v_mov_b32_e32 v80, v0
	v_mov_b32_e32 v81, v0
	v_mov_b32_e32 v82, v0
	v_mov_b32_e32 v83, v0
	v_mov_b32_e32 v84, v0
	v_mov_b32_e32 v85, v0
	v_mov_b32_e32 v86, v0
	v_mov_b32_e32 v87, v0
	v_mov_b32_e32 v96, v0
	v_mov_b32_e32 v97, v0
	v_mov_b32_e32 v98, v0
	v_mov_b32_e32 v99, v0
	v_mov_b32_e32 v100, v0
	v_mov_b32_e32 v101, v0
	v_mov_b32_e32 v102, v0
	v_mov_b32_e32 v103, v0
	v_mov_b32_e32 v112, v0
	v_mov_b32_e32 v113, v0
	v_mov_b32_e32 v114, v0
	v_mov_b32_e32 v115, v0
	v_mov_b32_e32 v116, v0
	v_mov_b32_e32 v117, v0
	v_mov_b32_e32 v118, v0
	v_mov_b32_e32 v119, v0
.LBB0_736:
	ds_read_b128 v[144:147], v149
	ds_read_b128 v[154:157], v149 offset:1024
	ds_read_b128 v[158:161], v149 offset:2048
	ds_read_b128 v[162:165], v149 offset:3072
	ds_read_b128 v[168:171], v150
	ds_read_b128 v[172:175], v150 offset:1024
	ds_read_b128 v[176:179], v150 offset:2048
	ds_read_b128 v[180:183], v150 offset:3072
	s_add_u32 s4, s28, 0xfff80080
	s_addc_u32 s5, s29, -1
	s_cmp_eq_u32 s60, 28
	s_cselect_b32 s35, s19, s5
	s_cselect_b32 s34, s56, s4
	s_cselect_b32 s31, s17, s59
	s_cselect_b32 s30, s57, s58
	v_lshl_add_u64 v[216:217], s[28:29], 0, v[136:137]
	s_add_i32 m0, s27, 0xc000
	ds_read_b128 v[184:187], v151
	ds_read_b128 v[188:191], v151 offset:1024
	ds_read_b128 v[192:195], v151 offset:2048
	ds_read_b128 v[196:199], v151 offset:3072
	ds_read_b128 v[200:203], v151 offset:4096
	ds_read_b128 v[204:207], v151 offset:5120
	ds_read_b128 v[208:211], v151 offset:6144
	ds_read_b128 v[212:215], v151 offset:7168
	global_load_lds_dwordx4 v[216:217], off
	v_lshl_add_u64 v[216:217], s[28:29], 0, v[138:139]
	s_add_i32 m0, s27, 0xe000
	s_nop 0
	global_load_lds_dwordx4 v[216:217], off
	s_waitcnt vmcnt(8)
	s_waitcnt lgkmcnt(0)
	s_barrier
; #define PG8_STAGE(bufoff, gbase, voff) do { _Pragma("unroll") for (int _i = 0; _i < 2; ++_i) \
;         __builtin_amdgcn_global_load_lds((const unsigned*)((const char*)(gbase) + (voff)[_i]), (PG8_LAS unsigned*)(lds + (bufoff) + ldsw + _i * 8192), 16, 0, 0); } while (0)
; #define PG8_LDA(dst, b, h) do { _Pragma("unroll") for (int m = 0; m < 4; ++m) _Pragma("unroll") for (int k = 0; k < 2; ++k) dst[m][k] = *(const PG8_LAS bf16x8*)(lds + PG8_SA(b, h) + aoff + m * 2048 + k * 1024); } while (0)
; #define PG8_MMA(ai, bj, At, Bt) do { __builtin_amdgcn_s_setprio(1); _Pragma("unroll") for (int m = 0; m < 4; ++m) _Pragma("unroll") for (int n = 0; n < 2; ++n) _Pragma("unroll") for (int k = 0; k < 2; ++k) \
;         acc[ai][bj][m][n] = __builtin_amdgcn_mfma_f32_16x16x32_bf16(Bt[n][k], At[m][k], acc[ai][bj][m][n], 0, 0, 0); __builtin_amdgcn_s_setprio(0); } while (0)
; #define PG8_WAIT_V(n) asm volatile("s_waitcnt vmcnt(" #n ")" ::: "memory")
; #define PG8_WAIT_L(n) asm volatile("s_waitcnt lgkmcnt(" #n ")" ::: "memory")
; #define PG8_BAR __builtin_amdgcn_s_barrier()
; #define PG8_SCHED __builtin_amdgcn_sched_barrier(0)
; template <class Epi, class Sched, bool ALIGN_EPI = false, bool SP2 = false>
; __device__ __forceinline__ void gemm_phase(PG8_LAS unsigned char* lds, const Gemm g, const Sched& S, const Epi& E) {
;     ...
;             PG8_WAIT_V(8); PG8_WAIT_L(0); PG8_BAR; PG8_MMA(0, 0, At, B0); PG8_MMA(0, 1, At, B1); PG8_BAR; PG8_SCHED;
;             PG8_LDA(At, 0, 1); PG8_STAGE(PG8_SB(0, 0), b2, voffB); PG8_STAGE(PG8_SB(0, 1), b2 + hstepB, voffB); PG8_STAGE(PG8_SA(0, 0), a2, voffA);
;             PG8_WAIT_V(8); PG8_WAIT_L(0); PG8_BAR; PG8_MMA(1, 0, At, B0); PG8_MMA(1, 1, At, B1); PG8_BAR; PG8_SCHED;
	s_setprio 1
	s_waitcnt lgkmcnt(0)
	v_mfma_f32_16x16x32_bf16 v[116:119], v[144:147], v[184:187], v[116:119]
	v_mfma_f32_16x16x32_bf16 v[112:115], v[158:161], v[184:187], v[112:115]
	v_mfma_f32_16x16x32_bf16 v[100:103], v[144:147], v[192:195], v[100:103]
	v_mfma_f32_16x16x32_bf16 v[96:99], v[158:161], v[192:195], v[96:99]
	v_mfma_f32_16x16x32_bf16 v[84:87], v[144:147], v[200:203], v[84:87]
	v_mfma_f32_16x16x32_bf16 v[80:83], v[158:161], v[200:203], v[80:83]
	v_mfma_f32_16x16x32_bf16 v[68:71], v[144:147], v[208:211], v[68:71]
	v_mfma_f32_16x16x32_bf16 v[64:67], v[158:161], v[208:211], v[64:67]
	v_mfma_f32_16x16x32_bf16 v[116:119], v[154:157], v[188:191], v[116:119]
	v_mfma_f32_16x16x32_bf16 v[112:115], v[162:165], v[188:191], v[112:115]
	v_mfma_f32_16x16x32_bf16 v[100:103], v[154:157], v[196:199], v[100:103]
	v_mfma_f32_16x16x32_bf16 v[96:99], v[162:165], v[196:199], v[96:99]
	v_mfma_f32_16x16x32_bf16 v[84:87], v[154:157], v[204:207], v[84:87]
	v_mfma_f32_16x16x32_bf16 v[80:83], v[162:165], v[204:207], v[80:83]
	v_mfma_f32_16x16x32_bf16 v[68:71], v[154:157], v[212:215], v[68:71]
	v_mfma_f32_16x16x32_bf16 v[64:67], v[162:165], v[212:215], v[64:67]
	s_setprio 0
	s_setprio 1
	v_mfma_f32_16x16x32_bf16 v[124:127], v[168:171], v[184:187], v[124:127]
	v_mfma_f32_16x16x32_bf16 v[120:123], v[176:179], v[184:187], v[120:123]
	v_mfma_f32_16x16x32_bf16 v[108:111], v[168:171], v[192:195], v[108:111]
	v_mfma_f32_16x16x32_bf16 v[104:107], v[176:179], v[192:195], v[104:107]
	v_mfma_f32_16x16x32_bf16 v[92:95], v[168:171], v[200:203], v[92:95]
	v_mfma_f32_16x16x32_bf16 v[88:91], v[176:179], v[200:203], v[88:91]
	v_mfma_f32_16x16x32_bf16 v[76:79], v[168:171], v[208:211], v[76:79]
	v_mfma_f32_16x16x32_bf16 v[72:75], v[176:179], v[208:211], v[72:75]
	v_mfma_f32_16x16x32_bf16 v[124:127], v[172:175], v[188:191], v[124:127]
	v_mfma_f32_16x16x32_bf16 v[120:123], v[180:183], v[188:191], v[120:123]
	v_mfma_f32_16x16x32_bf16 v[108:111], v[172:175], v[196:199], v[108:111]
	v_mfma_f32_16x16x32_bf16 v[104:107], v[180:183], v[196:199], v[104:107]
	v_mfma_f32_16x16x32_bf16 v[92:95], v[172:175], v[204:207], v[92:95]
	v_mfma_f32_16x16x32_bf16 v[88:91], v[180:183], v[204:207], v[88:91]
	v_mfma_f32_16x16x32_bf16 v[76:79], v[172:175], v[212:215], v[76:79]
	v_mfma_f32_16x16x32_bf16 v[72:75], v[180:183], v[212:215], v[72:75]
	s_setprio 0
	s_barrier
	s_add_i32 s4, s41, s47
	v_lshl_add_u64 v[216:217], s[30:31], 0, v[132:133]
	s_mov_b32 m0, s4
	ds_read_b128 v[184:187], v151 offset:16384
	ds_read_b128 v[188:191], v151 offset:17408
	ds_read_b128 v[192:195], v151 offset:18432
	ds_read_b128 v[196:199], v151 offset:19456
	ds_read_b128 v[200:203], v151 offset:20480
	ds_read_b128 v[204:207], v151 offset:21504
	ds_read_b128 v[208:211], v151 offset:22528
	ds_read_b128 v[212:215], v151 offset:23552
	global_load_lds_dwordx4 v[216:217], off
	s_add_i32 m0, s4, 0x2000
	s_add_u32 s4, s30, 0x80000
	v_lshl_add_u64 v[218:219], s[30:31], 0, v[128:129]
	s_addc_u32 s5, s31, 0
	s_add_i32 s61, s44, s47
	global_load_lds_dwordx4 v[218:219], off
	v_lshl_add_u64 v[220:221], s[4:5], 0, v[132:133]
	s_mov_b32 m0, s61
	v_lshl_add_u64 v[222:223], s[34:35], 0, v[130:131]
	global_load_lds_dwordx4 v[220:221], off
	v_lshl_add_u64 v[220:221], s[4:5], 0, v[128:129]
	s_add_i32 m0, s61, 0x2000
	s_nop 0
	global_load_lds_dwordx4 v[220:221], off
	v_lshl_add_u64 v[220:221], s[34:35], 0, v[134:135]
	s_mov_b32 m0, s27
	s_nop 0
	global_load_lds_dwordx4 v[220:221], off
	s_mov_b32 m0, s33
	s_nop 0
	global_load_lds_dwordx4 v[222:223], off
	s_waitcnt vmcnt(8)
	s_waitcnt lgkmcnt(0)
	s_barrier
	s_setprio 1
	s_waitcnt lgkmcnt(0)
	v_mfma_f32_16x16x32_bf16 v[52:55], v[144:147], v[184:187], v[52:55]
	v_mfma_f32_16x16x32_bf16 v[48:51], v[158:161], v[184:187], v[48:51]
	v_mfma_f32_16x16x32_bf16 v[36:39], v[144:147], v[192:195], v[36:39]
	v_mfma_f32_16x16x32_bf16 v[32:35], v[158:161], v[192:195], v[32:35]
	v_mfma_f32_16x16x32_bf16 v[20:23], v[144:147], v[200:203], v[20:23]
	v_mfma_f32_16x16x32_bf16 v[16:19], v[158:161], v[200:203], v[16:19]
	v_mfma_f32_16x16x32_bf16 v[8:11], v[144:147], v[208:211], v[8:11]
	v_mfma_f32_16x16x32_bf16 v[4:7], v[158:161], v[208:211], v[4:7]
	v_mfma_f32_16x16x32_bf16 v[52:55], v[154:157], v[188:191], v[52:55]
	v_mfma_f32_16x16x32_bf16 v[48:51], v[162:165], v[188:191], v[48:51]
	v_mfma_f32_16x16x32_bf16 v[36:39], v[154:157], v[196:199], v[36:39]
	v_mfma_f32_16x16x32_bf16 v[32:35], v[162:165], v[196:199], v[32:35]
	v_mfma_f32_16x16x32_bf16 v[20:23], v[154:157], v[204:207], v[20:23]
	v_mfma_f32_16x16x32_bf16 v[16:19], v[162:165], v[204:207], v[16:19]
	v_mfma_f32_16x16x32_bf16 v[8:11], v[154:157], v[212:215], v[8:11]
	v_mfma_f32_16x16x32_bf16 v[4:7], v[162:165], v[212:215], v[4:7]
	s_setprio 0
	s_setprio 1
	v_mfma_f32_16x16x32_bf16 v[60:63], v[168:171], v[184:187], v[60:63]
	v_mfma_f32_16x16x32_bf16 v[56:59], v[176:179], v[184:187], v[56:59]
	v_mfma_f32_16x16x32_bf16 v[44:47], v[168:171], v[192:195], v[44:47]
	v_mfma_f32_16x16x32_bf16 v[40:43], v[176:179], v[192:195], v[40:43]
	v_mfma_f32_16x16x32_bf16 v[28:31], v[168:171], v[200:203], v[28:31]
	v_mfma_f32_16x16x32_bf16 v[24:27], v[176:179], v[200:203], v[24:27]
	v_mfma_f32_16x16x32_bf16 v[12:15], v[168:171], v[208:211], v[12:15]
	v_mfma_f32_16x16x32_bf16 v[0:3], v[176:179], v[208:211], v[0:3]
	v_mfma_f32_16x16x32_bf16 v[60:63], v[172:175], v[188:191], v[60:63]
	v_mfma_f32_16x16x32_bf16 v[56:59], v[180:183], v[188:191], v[56:59]
	v_mfma_f32_16x16x32_bf16 v[44:47], v[172:175], v[196:199], v[44:47]
	v_mfma_f32_16x16x32_bf16 v[40:43], v[180:183], v[196:199], v[40:43]
	v_mfma_f32_16x16x32_bf16 v[28:31], v[172:175], v[204:207], v[28:31]
	v_mfma_f32_16x16x32_bf16 v[24:27], v[180:183], v[204:207], v[24:27]
	v_mfma_f32_16x16x32_bf16 v[12:15], v[172:175], v[212:215], v[12:15]
	v_mfma_f32_16x16x32_bf16 v[0:3], v[180:183], v[212:215], v[0:3]
	s_setprio 0
	s_barrier
; #define PG8_STAGE(bufoff, gbase, voff) do { _Pragma("unroll") for (int _i = 0; _i < 2; ++_i) \
;         __builtin_amdgcn_global_load_lds((const unsigned*)((const char*)(gbase) + (voff)[_i]), (PG8_LAS unsigned*)(lds + (bufoff) + ldsw + _i * 8192), 16, 0, 0); } while (0)
; #define PG8_LDA(dst, b, h) do { _Pragma("unroll") for (int m = 0; m < 4; ++m) _Pragma("unroll") for (int k = 0; k < 2; ++k) dst[m][k] = *(const PG8_LAS bf16x8*)(lds + PG8_SA(b, h) + aoff + m * 2048 + k * 1024); } while (0)
; #define PG8_LDB(dst, b, h) do { _Pragma("unroll") for (int n = 0; n < 2; ++n) _Pragma("unroll") for (int k = 0; k < 2; ++k) dst[n][k] = *(const PG8_LAS bf16x8*)(lds + PG8_SB(b, h) + boff + n * 2048 + k * 1024); } while (0)
; #define PG8_MMA(ai, bj, At, Bt) do { __builtin_amdgcn_s_setprio(1); _Pragma("unroll") for (int m = 0; m < 4; ++m) _Pragma("unroll") for (int n = 0; n < 2; ++n) _Pragma("unroll") for (int k = 0; k < 2; ++k) \
;         acc[ai][bj][m][n] = __builtin_amdgcn_mfma_f32_16x16x32_bf16(Bt[n][k], At[m][k], acc[ai][bj][m][n], 0, 0, 0); __builtin_amdgcn_s_setprio(0); } while (0)
; #define PG8_WAIT_V(n) asm volatile("s_waitcnt vmcnt(" #n ")" ::: "memory")
; #define PG8_WAIT_L(n) asm volatile("s_waitcnt lgkmcnt(" #n ")" ::: "memory")
; #define PG8_BAR __builtin_amdgcn_s_barrier()
; #define PG8_SCHED __builtin_amdgcn_sched_barrier(0)
; template <class Epi, class Sched, bool ALIGN_EPI = false, bool SP2 = false>
; __device__ __forceinline__ void gemm_phase(PG8_LAS unsigned char* lds, const Gemm g, const Sched& S, const Epi& E) {
;     ...
;             PG8_LDB(B0, 1, 0); PG8_LDB(B1, 1, 1); PG8_SCHED; PG8_LDA(At, 1, 0); PG8_STAGE(PG8_SA(0, 1), a2 + hstepA, voffA);
;             PG8_WAIT_V(8); PG8_WAIT_L(0); PG8_BAR; PG8_MMA(0, 0, At, B0); PG8_MMA(0, 1, At, B1); PG8_BAR; PG8_SCHED;
;             PG8_LDA(At, 1, 1); PG8_STAGE(PG8_SB(1, 0), b3, voffB); PG8_STAGE(PG8_SB(1, 1), b3 + hstepB, voffB); PG8_STAGE(PG8_SA(1, 0), a3, voffA);
	s_add_i32 s61, 0, 0x18000
	v_add_u32_e32 v153, s61, v148
	s_add_i32 s62, 0, 0x1c000
	ds_read_b128 v[144:147], v153
	ds_read_b128 v[154:157], v153 offset:1024
	ds_read_b128 v[158:161], v153 offset:2048
	ds_read_b128 v[162:165], v153 offset:3072
	v_add_u32_e32 v153, s62, v148
	ds_read_b128 v[168:171], v153
	ds_read_b128 v[172:175], v153 offset:1024
	ds_read_b128 v[176:179], v153 offset:2048
	ds_read_b128 v[180:183], v153 offset:3072
	s_add_u32 s4, s34, 0x80000
	s_addc_u32 s5, s35, 0
	s_mov_b32 m0, s36
	v_lshl_add_u64 v[224:225], s[4:5], 0, v[134:135]
	ds_read_b128 v[184:187], v151 offset:32768
	ds_read_b128 v[188:191], v151 offset:33792
	ds_read_b128 v[192:195], v151 offset:34816
	ds_read_b128 v[196:199], v151 offset:35840
	ds_read_b128 v[200:203], v151 offset:36864
	ds_read_b128 v[204:207], v151 offset:37888
	ds_read_b128 v[208:211], v151 offset:38912
	ds_read_b128 v[212:215], v151 offset:39936
	global_load_lds_dwordx4 v[224:225], off
	v_lshl_add_u64 v[224:225], s[4:5], 0, v[130:131]
	s_mov_b32 m0, s37
	s_nop 0
	global_load_lds_dwordx4 v[224:225], off
	s_waitcnt vmcnt(8)
	s_waitcnt lgkmcnt(0)
	s_barrier
	s_setprio 1
	s_waitcnt lgkmcnt(0)
	v_mfma_f32_16x16x32_bf16 v[116:119], v[144:147], v[184:187], v[116:119]
	v_mfma_f32_16x16x32_bf16 v[112:115], v[158:161], v[184:187], v[112:115]
	v_mfma_f32_16x16x32_bf16 v[100:103], v[144:147], v[192:195], v[100:103]
	v_mfma_f32_16x16x32_bf16 v[96:99], v[158:161], v[192:195], v[96:99]
	v_mfma_f32_16x16x32_bf16 v[84:87], v[144:147], v[200:203], v[84:87]
	v_mfma_f32_16x16x32_bf16 v[80:83], v[158:161], v[200:203], v[80:83]
	v_mfma_f32_16x16x32_bf16 v[68:71], v[144:147], v[208:211], v[68:71]
	v_mfma_f32_16x16x32_bf16 v[64:67], v[158:161], v[208:211], v[64:67]
	v_mfma_f32_16x16x32_bf16 v[116:119], v[154:157], v[188:191], v[116:119]
	v_mfma_f32_16x16x32_bf16 v[112:115], v[162:165], v[188:191], v[112:115]
	v_mfma_f32_16x16x32_bf16 v[100:103], v[154:157], v[196:199], v[100:103]
	v_mfma_f32_16x16x32_bf16 v[96:99], v[162:165], v[196:199], v[96:99]
	v_mfma_f32_16x16x32_bf16 v[84:87], v[154:157], v[204:207], v[84:87]
	v_mfma_f32_16x16x32_bf16 v[80:83], v[162:165], v[204:207], v[80:83]
	v_mfma_f32_16x16x32_bf16 v[68:71], v[154:157], v[212:215], v[68:71]
	v_mfma_f32_16x16x32_bf16 v[64:67], v[162:165], v[212:215], v[64:67]
	s_setprio 0
	s_setprio 1
	v_mfma_f32_16x16x32_bf16 v[124:127], v[168:171], v[184:187], v[124:127]
	v_mfma_f32_16x16x32_bf16 v[120:123], v[176:179], v[184:187], v[120:123]
	v_mfma_f32_16x16x32_bf16 v[108:111], v[168:171], v[192:195], v[108:111]
	v_mfma_f32_16x16x32_bf16 v[104:107], v[176:179], v[192:195], v[104:107]
	v_mfma_f32_16x16x32_bf16 v[92:95], v[168:171], v[200:203], v[92:95]
	v_mfma_f32_16x16x32_bf16 v[88:91], v[176:179], v[200:203], v[88:91]
	v_mfma_f32_16x16x32_bf16 v[76:79], v[168:171], v[208:211], v[76:79]
	v_mfma_f32_16x16x32_bf16 v[72:75], v[176:179], v[208:211], v[72:75]
	v_mfma_f32_16x16x32_bf16 v[124:127], v[172:175], v[188:191], v[124:127]
	v_mfma_f32_16x16x32_bf16 v[120:123], v[180:183], v[188:191], v[120:123]
	v_mfma_f32_16x16x32_bf16 v[108:111], v[172:175], v[196:199], v[108:111]
	v_mfma_f32_16x16x32_bf16 v[104:107], v[180:183], v[196:199], v[104:107]
	v_mfma_f32_16x16x32_bf16 v[92:95], v[172:175], v[204:207], v[92:95]
	v_mfma_f32_16x16x32_bf16 v[88:91], v[180:183], v[204:207], v[88:91]
	v_mfma_f32_16x16x32_bf16 v[76:79], v[172:175], v[212:215], v[76:79]
	v_mfma_f32_16x16x32_bf16 v[72:75], v[180:183], v[212:215], v[72:75]
	s_setprio 0
	s_barrier
	s_add_i32 s4, s61, s47
	v_lshl_add_u64 v[216:217], v[216:217], 0, s[14:15]
	s_mov_b32 m0, s4
	ds_read_b128 v[184:187], v151 offset:49152
	ds_read_b128 v[188:191], v151 offset:50176
	ds_read_b128 v[192:195], v151 offset:51200
	ds_read_b128 v[196:199], v151 offset:52224
	ds_read_b128 v[200:203], v151 offset:53248
	ds_read_b128 v[204:207], v151 offset:54272
	ds_read_b128 v[208:211], v151 offset:55296
	ds_read_b128 v[212:215], v151 offset:56320
	global_load_lds_dwordx4 v[216:217], off
	s_add_i32 m0, s4, 0x2000
	s_add_u32 s4, s30, 0x80080
	v_lshl_add_u64 v[216:217], v[218:219], 0, s[14:15]
	s_addc_u32 s5, s31, 0
	s_add_i32 s30, s62, s47
	global_load_lds_dwordx4 v[216:217], off
	v_lshl_add_u64 v[216:217], s[4:5], 0, v[132:133]
	s_mov_b32 m0, s30
	s_nop 0
	global_load_lds_dwordx4 v[216:217], off
	v_lshl_add_u64 v[216:217], s[4:5], 0, v[128:129]
	s_add_i32 m0, s30, 0x2000
	s_nop 0
	global_load_lds_dwordx4 v[216:217], off
	v_lshl_add_u64 v[216:217], v[220:221], 0, s[14:15]
	s_mov_b32 m0, s39
	s_nop 0
	global_load_lds_dwordx4 v[216:217], off
	v_lshl_add_u64 v[216:217], v[222:223], 0, s[14:15]
	s_mov_b32 m0, s40
	s_nop 0
	global_load_lds_dwordx4 v[216:217], off
	s_waitcnt vmcnt(8)
	s_waitcnt lgkmcnt(0)
	s_barrier
; #define PG8_LDA(dst, b, h) do { _Pragma("unroll") for (int m = 0; m < 4; ++m) _Pragma("unroll") for (int k = 0; k < 2; ++k) dst[m][k] = *(const PG8_LAS bf16x8*)(lds + PG8_SA(b, h) + aoff + m * 2048 + k * 1024); } while (0)
; template <class Epi, class Sched, bool ALIGN_EPI = false, bool SP2 = false>
; __device__ __forceinline__ void gemm_phase(PG8_LAS unsigned char* lds, const Gemm g, const Sched& S, const Epi& E) {
;     ...
;             PG8_WAIT_V(8); PG8_WAIT_L(0); PG8_BAR; PG8_MMA(1, 0, At, B0); PG8_MMA(1, 1, At, B1); PG8_BAR; PG8_SCHED;
;             } else {
;             PG8_LDB(B0, 0, 0); PG8_SCHED; PG8_LDA(At, 0, 0); PG8_STAGE(PG8_SA(1, 1), a1 + hstepA, voffA);
;             PG8_WAIT_L(8); PG8_BAR; PG8_WAIT_L(0); PG8_MMA(0, 0, At, B0); PG8_BAR; PG8_SCHED;
;             PG8_LDB(B1, 0, 1); PG8_STAGE(PG8_SB(0, 0), b2, voffB);
;             PG8_BAR; PG8_WAIT_L(0); PG8_MMA(0, 1, At, B1); PG8_BAR;
;             PG8_LDA(At, 0, 1); PG8_STAGE(PG8_SA(0, 0), a2, voffA);
;             PG8_BAR; PG8_WAIT_L(0); PG8_MMA(1, 0, At, B0); PG8_BAR; PG8_SCHED;
;             PG8_STAGE(PG8_SB(0, 1), b2 + hstepB, voffB);
;             PG8_WAIT_V(6); PG8_BAR; PG8_MMA(1, 1, At, B1); PG8_BAR;
;             PG8_LDB(B0, 1, 0); PG8_SCHED; PG8_LDA(At, 1, 0); PG8_STAGE(PG8_SA(0, 1), a2 + hstepA, voffA);
;             PG8_WAIT_L(8); PG8_BAR; PG8_WAIT_L(0); PG8_MMA(0, 0, At, B0); PG8_BAR; PG8_SCHED;
;             PG8_LDB(B1, 1, 1); PG8_STAGE(PG8_SB(1, 0), b3, voffB);
;             PG8_BAR; PG8_WAIT_L(0); PG8_MMA(0, 1, At, B1); PG8_BAR;
;             PG8_LDA(At, 1, 1); PG8_STAGE(PG8_SA(1, 0), a3, voffA);
;             PG8_BAR; PG8_WAIT_L(0); PG8_MMA(1, 0, At, B0); PG8_BAR; PG8_SCHED;
;             PG8_STAGE(PG8_SB(1, 1), b3 + hstepB, voffB);
;             PG8_WAIT_V(6); PG8_BAR; PG8_MMA(1, 1, At, B1); PG8_BAR;
;             }
;         }
;         if constexpr (ALIGN_EPI) { if (wr == 0) PG8_BAR; }
;     __device__ __forceinline__ void operator()(const f32x4 (&acc)[2][2][4][2], const Unit& u, int wr, int wc, int fr, int fq) const {
;     ...
;             for (int m = 0; m < 4; ++m) { const int row = row0 + ai * HALF + m * 16; const float rs = row_rstd(ssq, row, fr, fq), rs2 = rs * rs, nrl = -1.4426950408889634f * rs;
;                 float o[8];
; #pragma unroll
;                 for (int n = 0; n < 2; ++n) { const f32x4 g = acc[ai][0][m][n], gu = g * acc[ai][1][m][n] * rs2;
	s_setprio 1
	s_waitcnt lgkmcnt(0)
	v_mfma_f32_16x16x32_bf16 v[52:55], v[144:147], v[184:187], v[52:55]
	v_mfma_f32_16x16x32_bf16 v[48:51], v[158:161], v[184:187], v[48:51]
	v_mfma_f32_16x16x32_bf16 v[36:39], v[144:147], v[192:195], v[36:39]
	v_mfma_f32_16x16x32_bf16 v[32:35], v[158:161], v[192:195], v[32:35]
	v_mfma_f32_16x16x32_bf16 v[20:23], v[144:147], v[200:203], v[20:23]
	v_mfma_f32_16x16x32_bf16 v[16:19], v[158:161], v[200:203], v[16:19]
	v_mfma_f32_16x16x32_bf16 v[8:11], v[144:147], v[208:211], v[8:11]
	v_mfma_f32_16x16x32_bf16 v[4:7], v[158:161], v[208:211], v[4:7]
	v_mfma_f32_16x16x32_bf16 v[52:55], v[154:157], v[188:191], v[52:55]
	v_mfma_f32_16x16x32_bf16 v[48:51], v[162:165], v[188:191], v[48:51]
	v_mfma_f32_16x16x32_bf16 v[36:39], v[154:157], v[196:199], v[36:39]
	v_mfma_f32_16x16x32_bf16 v[32:35], v[162:165], v[196:199], v[32:35]
	v_mfma_f32_16x16x32_bf16 v[20:23], v[154:157], v[204:207], v[20:23]
	v_mfma_f32_16x16x32_bf16 v[16:19], v[162:165], v[204:207], v[16:19]
	v_mfma_f32_16x16x32_bf16 v[8:11], v[154:157], v[212:215], v[8:11]
	v_mfma_f32_16x16x32_bf16 v[4:7], v[162:165], v[212:215], v[4:7]
	s_setprio 0
	s_setprio 1
	v_mfma_f32_16x16x32_bf16 v[60:63], v[168:171], v[184:187], v[60:63]
	v_mfma_f32_16x16x32_bf16 v[56:59], v[176:179], v[184:187], v[56:59]
	v_mfma_f32_16x16x32_bf16 v[44:47], v[168:171], v[192:195], v[44:47]
	v_mfma_f32_16x16x32_bf16 v[40:43], v[176:179], v[192:195], v[40:43]
	v_mfma_f32_16x16x32_bf16 v[28:31], v[168:171], v[200:203], v[28:31]
	v_mfma_f32_16x16x32_bf16 v[24:27], v[176:179], v[200:203], v[24:27]
	v_mfma_f32_16x16x32_bf16 v[12:15], v[168:171], v[208:211], v[12:15]
	v_mfma_f32_16x16x32_bf16 v[0:3], v[176:179], v[208:211], v[0:3]
	v_mfma_f32_16x16x32_bf16 v[60:63], v[172:175], v[188:191], v[60:63]
	v_mfma_f32_16x16x32_bf16 v[56:59], v[180:183], v[188:191], v[56:59]
	v_mfma_f32_16x16x32_bf16 v[44:47], v[172:175], v[196:199], v[44:47]
	v_mfma_f32_16x16x32_bf16 v[40:43], v[180:183], v[196:199], v[40:43]
	v_mfma_f32_16x16x32_bf16 v[28:31], v[172:175], v[204:207], v[28:31]
	v_mfma_f32_16x16x32_bf16 v[24:27], v[180:183], v[204:207], v[24:27]
	v_mfma_f32_16x16x32_bf16 v[12:15], v[172:175], v[212:215], v[12:15]
	v_mfma_f32_16x16x32_bf16 v[0:3], v[180:183], v[212:215], v[0:3]
	s_setprio 0
	s_barrier
	s_add_i32 s60, s60, 2
	s_add_u32 s28, s28, 0x100
	s_addc_u32 s29, s29, 0
	s_add_u32 s58, s58, 0x100
	s_addc_u32 s59, s59, 0
	s_cmp_gt_u32 s60, 29
	s_cbranch_scc0 .LBB0_736
	s_and_b64 vcc, exec, s[48:49]
	s_cbranch_vccz .LBB0_739
	s_barrier
.LBB0_739:
	v_and_b32_e32 v153, 15, v167
	v_lshrrev_b32_e32 v154, 4, v167
	s_lshl_b32 s4, s26, 8
	s_add_i32 s4, s4, s78
	v_or_b32_e32 v155, s4, v153
	v_lshlrev_b32_e32 v156, 7, v155
	v_lshl_add_u32 v156, v154, 5, v156
	v_add_u32_e32 v157, 0x1000, v156
	v_add_u32_e32 v158, 0x4000, v156
	v_add_u32_e32 v159, 0x5000, v156
	global_load_dwordx4 v[168:171], v156, s[12:13]
	global_load_dwordx4 v[172:175], v156, s[12:13] offset:16
	global_load_dwordx4 v[176:179], v156, s[12:13] offset:2048
	global_load_dwordx4 v[180:183], v156, s[12:13] offset:2064
	global_load_dwordx4 v[184:187], v157, s[12:13]
	global_load_dwordx4 v[188:191], v157, s[12:13] offset:16
	global_load_dwordx4 v[192:195], v157, s[12:13] offset:2048
	global_load_dwordx4 v[196:199], v157, s[12:13] offset:2064
	global_load_dwordx4 v[200:203], v158, s[12:13]
	global_load_dwordx4 v[204:207], v158, s[12:13] offset:16
	global_load_dwordx4 v[208:211], v158, s[12:13] offset:2048
	global_load_dwordx4 v[212:215], v158, s[12:13] offset:2064
	global_load_dwordx4 v[216:219], v159, s[12:13]
	global_load_dwordx4 v[220:223], v159, s[12:13] offset:16
	global_load_dwordx4 v[224:227], v159, s[12:13] offset:2048
	global_load_dwordx4 v[228:231], v159, s[12:13] offset:2064
	v_xor_b32_e32 v160, 16, v167
	v_xor_b32_e32 v161, 32, v167
	v_lshlrev_b32_e32 v160, 2, v160
	v_lshlrev_b32_e32 v161, 2, v161
	s_lshl_b32 s4, s55, 7
	s_or_b32 s4, s4, s82
	v_lshl_add_u32 v162, v154, 3, s4
	v_lshlrev_b32_e32 v162, 1, v162
	v_mul_u32_u24_e32 v163, 0x2c00, v155
	v_add_u32_e32 v162, v162, v163
	v_mul_f32_e32 v124, v116, v124
	v_mul_f32_e32 v125, v117, v125
	v_mul_f32_e32 v126, v118, v126
	v_mul_f32_e32 v127, v119, v127
	v_mul_f32_e32 v120, v112, v120
	v_mul_f32_e32 v121, v113, v121
	v_mul_f32_e32 v122, v114, v122
	v_mul_f32_e32 v123, v115, v123
	v_mul_f32_e32 v108, v100, v108
	v_mul_f32_e32 v109, v101, v109
	v_mul_f32_e32 v110, v102, v110
	v_mul_f32_e32 v111, v103, v111
	v_mul_f32_e32 v104, v96, v104
	v_mul_f32_e32 v105, v97, v105
	v_mul_f32_e32 v106, v98, v106
	v_mul_f32_e32 v107, v99, v107
	v_mul_f32_e32 v92, v84, v92
	v_mul_f32_e32 v93, v85, v93
	v_mul_f32_e32 v94, v86, v94
	v_mul_f32_e32 v95, v87, v95
	v_mul_f32_e32 v88, v80, v88
	v_mul_f32_e32 v89, v81, v89
	v_mul_f32_e32 v90, v82, v90
	v_mul_f32_e32 v91, v83, v91
	v_mul_f32_e32 v76, v68, v76
	v_mul_f32_e32 v77, v69, v77
	v_mul_f32_e32 v78, v70, v78
	v_mul_f32_e32 v79, v71, v79
	v_mul_f32_e32 v72, v64, v72
	v_mul_f32_e32 v73, v65, v73
	v_mul_f32_e32 v74, v66, v74
	v_mul_f32_e32 v75, v67, v75
	v_mul_f32_e32 v60, v52, v60
	v_mul_f32_e32 v61, v53, v61
	v_mul_f32_e32 v62, v54, v62
	v_mul_f32_e32 v63, v55, v63
	v_mul_f32_e32 v56, v48, v56
	v_mul_f32_e32 v57, v49, v57
	v_mul_f32_e32 v58, v50, v58
	v_mul_f32_e32 v59, v51, v59
	v_mul_f32_e32 v44, v36, v44
	v_mul_f32_e32 v45, v37, v45
	v_mul_f32_e32 v46, v38, v46
	v_mul_f32_e32 v47, v39, v47
	v_mul_f32_e32 v40, v32, v40
	v_mul_f32_e32 v41, v33, v41
	v_mul_f32_e32 v42, v34, v42
	v_mul_f32_e32 v43, v35, v43
	v_mul_f32_e32 v28, v20, v28
	v_mul_f32_e32 v29, v21, v29
	v_mul_f32_e32 v30, v22, v30
	v_mul_f32_e32 v31, v23, v31
	v_mul_f32_e32 v24, v16, v24
	v_mul_f32_e32 v25, v17, v25
	v_mul_f32_e32 v26, v18, v26
	v_mul_f32_e32 v27, v19, v27
	v_mul_f32_e32 v12, v8, v12
	v_mul_f32_e32 v13, v9, v13
	v_mul_f32_e32 v14, v10, v14
	v_mul_f32_e32 v15, v11, v15
	v_mul_f32_e32 v0, v4, v0
	v_mul_f32_e32 v1, v5, v1
	v_mul_f32_e32 v2, v6, v2
	v_mul_f32_e32 v3, v7, v3
	s_waitcnt vmcnt(0)
; __device__ __forceinline__ unsigned cvt_pk_bf16(float lo, float hi) { unsigned r; asm volatile("v_cvt_pk_bf16_f32 %0, %1, %2" : "=v"(r) : "v"(lo), "v"(hi)); return r; }
; __device__ __forceinline__ float shx(float v, int mask, int lane) { return __int_as_float(__builtin_amdgcn_ds_bpermute((lane ^ mask) << 2, __float_as_int(v))); }
; __device__ __forceinline__ float row_rstd(const float* ssqp, int row, int fr, int fq) {
;     const f32x4 p0 = *(const f32x4*)(ssqp + (size_t)row * 32 + fq * 8), p1 = *(const f32x4*)(ssqp + (size_t)row * 32 + fq * 8 + 4);
;     float t = ((p0[0] + p0[1]) + (p0[2] + p0[3])) + ((p1[0] + p1[1]) + (p1[2] + p1[3])); const int ln = fr + 16 * fq;
;     t += shx(t, 16, ln); t += shx(t, 32, ln);
;     return rsqrtf(t * (1.0f / 2048.0f) + RMS_EPS);
;     __device__ __forceinline__ void operator()(const f32x4 (&acc)[2][2][4][2], const Unit& u, int wr, int wc, int fr, int fq) const {
;     ...
;             for (int m = 0; m < 4; ++m) { const int row = row0 + ai * HALF + m * 16; const float rs = row_rstd(ssq, row, fr, fq), rs2 = rs * rs, nrl = -1.4426950408889634f * rs;
;                 float o[8];
; #pragma unroll
;                 for (int n = 0; n < 2; ++n) { const f32x4 g = acc[ai][0][m][n], gu = g * acc[ai][1][m][n] * rs2;
; #pragma unroll
;                     for (int j = 0; j < 4; ++j) o[4 * n + j] = gu[j] * __builtin_amdgcn_rcpf(1.0f + __builtin_amdgcn_exp2f(g[j] * nrl)); }
;                 u32x4 w; w.x = cvt_pk_bf16(o[0], o[1]); w.y = cvt_pk_bf16(o[2], o[3]); w.z = cvt_pk_bf16(o[4], o[5]); w.w = cvt_pk_bf16(o[6], o[7]);
;                 *(u32x4*)(ACT + (size_t)row * 5632 + ch0) = w;
	v_add_f32_e32 v168, v168, v169
	v_add_f32_e32 v176, v176, v177
	v_add_f32_e32 v184, v184, v185
	v_add_f32_e32 v192, v192, v193
	v_add_f32_e32 v200, v200, v201
	v_add_f32_e32 v208, v208, v209
	v_add_f32_e32 v216, v216, v217
	v_add_f32_e32 v224, v224, v225
	v_add_f32_e32 v170, v170, v171
	v_add_f32_e32 v178, v178, v179
	v_add_f32_e32 v186, v186, v187
	v_add_f32_e32 v194, v194, v195
	v_add_f32_e32 v202, v202, v203
	v_add_f32_e32 v210, v210, v211
	v_add_f32_e32 v218, v218, v219
	v_add_f32_e32 v226, v226, v227
	v_add_f32_e32 v172, v172, v173
	v_add_f32_e32 v180, v180, v181
	v_add_f32_e32 v188, v188, v189
	v_add_f32_e32 v196, v196, v197
	v_add_f32_e32 v204, v204, v205
	v_add_f32_e32 v212, v212, v213
	v_add_f32_e32 v220, v220, v221
	v_add_f32_e32 v228, v228, v229
	v_add_f32_e32 v174, v174, v175
	v_add_f32_e32 v182, v182, v183
	v_add_f32_e32 v190, v190, v191
	v_add_f32_e32 v198, v198, v199
	v_add_f32_e32 v206, v206, v207
	v_add_f32_e32 v214, v214, v215
	v_add_f32_e32 v222, v222, v223
	v_add_f32_e32 v230, v230, v231
	v_add_f32_e32 v168, v168, v170
	v_add_f32_e32 v176, v176, v178
	v_add_f32_e32 v184, v184, v186
	v_add_f32_e32 v192, v192, v194
	v_add_f32_e32 v200, v200, v202
	v_add_f32_e32 v208, v208, v210
	v_add_f32_e32 v216, v216, v218
	v_add_f32_e32 v224, v224, v226
	v_add_f32_e32 v172, v172, v174
	v_add_f32_e32 v180, v180, v182
	v_add_f32_e32 v188, v188, v190
	v_add_f32_e32 v196, v196, v198
	v_add_f32_e32 v204, v204, v206
	v_add_f32_e32 v212, v212, v214
	v_add_f32_e32 v220, v220, v222
	v_add_f32_e32 v228, v228, v230
	v_add_f32_e32 v168, v168, v172
	v_add_f32_e32 v176, v176, v180
	v_add_f32_e32 v184, v184, v188
	v_add_f32_e32 v192, v192, v196
	v_add_f32_e32 v200, v200, v204
	v_add_f32_e32 v208, v208, v212
	v_add_f32_e32 v216, v216, v220
	v_add_f32_e32 v224, v224, v228
	ds_bpermute_b32 v240, v160, v168
	ds_bpermute_b32 v241, v160, v176
	ds_bpermute_b32 v242, v160, v184
	ds_bpermute_b32 v243, v160, v192
	ds_bpermute_b32 v244, v160, v200
	ds_bpermute_b32 v245, v160, v208
	ds_bpermute_b32 v246, v160, v216
	ds_bpermute_b32 v247, v160, v224
	s_waitcnt lgkmcnt(0)
	v_add_f32_e32 v168, v168, v240
	v_add_f32_e32 v176, v176, v241
	v_add_f32_e32 v184, v184, v242
	v_add_f32_e32 v192, v192, v243
	v_add_f32_e32 v200, v200, v244
	v_add_f32_e32 v208, v208, v245
	v_add_f32_e32 v216, v216, v246
	v_add_f32_e32 v224, v224, v247
	ds_bpermute_b32 v240, v161, v168
	ds_bpermute_b32 v241, v161, v176
	ds_bpermute_b32 v242, v161, v184
	ds_bpermute_b32 v243, v161, v192
	ds_bpermute_b32 v244, v161, v200
	ds_bpermute_b32 v245, v161, v208
	ds_bpermute_b32 v246, v161, v216
	ds_bpermute_b32 v247, v161, v224
	s_waitcnt lgkmcnt(0)
	v_add_f32_e32 v168, v168, v240
	v_add_f32_e32 v176, v176, v241
	v_add_f32_e32 v184, v184, v242
	v_add_f32_e32 v192, v192, v243
	v_add_f32_e32 v200, v200, v244
	v_add_f32_e32 v208, v208, v245
	v_add_f32_e32 v216, v216, v246
	v_add_f32_e32 v224, v224, v247
	v_fmamk_f32 v168, v168, 0x3a000000, v152
	v_fmamk_f32 v176, v176, 0x3a000000, v152
	v_fmamk_f32 v184, v184, 0x3a000000, v152
	v_fmamk_f32 v192, v192, 0x3a000000, v152
	v_fmamk_f32 v200, v200, 0x3a000000, v152
	v_fmamk_f32 v208, v208, 0x3a000000, v152
	v_fmamk_f32 v216, v216, 0x3a000000, v152
	v_fmamk_f32 v224, v224, 0x3a000000, v152
	v_rsq_f32_e32 v232, v168
	v_rsq_f32_e32 v233, v176
	v_rsq_f32_e32 v234, v184
	v_rsq_f32_e32 v235, v192
	v_rsq_f32_e32 v236, v200
	v_rsq_f32_e32 v237, v208
	v_rsq_f32_e32 v238, v216
	v_rsq_f32_e32 v239, v224
	v_mul_f32_e32 v169, 0xbfb8aa3b, v232
	v_mul_f32_e32 v177, 0xbfb8aa3b, v233
	v_mul_f32_e32 v185, 0xbfb8aa3b, v234
	v_mul_f32_e32 v193, 0xbfb8aa3b, v235
	v_mul_f32_e32 v201, 0xbfb8aa3b, v236
	v_mul_f32_e32 v209, 0xbfb8aa3b, v237
	v_mul_f32_e32 v217, 0xbfb8aa3b, v238
	v_mul_f32_e32 v225, 0xbfb8aa3b, v239
	v_mul_f32_e32 v170, v232, v232
	v_mul_f32_e32 v178, v233, v233
	v_mul_f32_e32 v186, v234, v234
	v_mul_f32_e32 v194, v235, v235
	v_mul_f32_e32 v202, v236, v236
	v_mul_f32_e32 v210, v237, v237
	v_mul_f32_e32 v218, v238, v238
	v_mul_f32_e32 v226, v239, v239
	v_mov_b32_e32 v171, v162
	v_mul_f32_e32 v116, v116, v169
	v_mul_f32_e32 v117, v117, v169
	v_mul_f32_e32 v118, v118, v169
	v_mul_f32_e32 v119, v119, v169
	v_mul_f32_e32 v112, v112, v169
	v_mul_f32_e32 v113, v113, v169
	v_mul_f32_e32 v114, v114, v169
	v_mul_f32_e32 v115, v115, v169
	v_exp_f32_e32 v116, v116
	v_exp_f32_e32 v117, v117
	v_exp_f32_e32 v118, v118
	v_exp_f32_e32 v119, v119
	v_exp_f32_e32 v112, v112
	v_exp_f32_e32 v113, v113
	v_exp_f32_e32 v114, v114
	v_exp_f32_e32 v115, v115
	v_add_f32_e32 v116, 1.0, v116
	v_add_f32_e32 v117, 1.0, v117
	v_add_f32_e32 v118, 1.0, v118
	v_add_f32_e32 v119, 1.0, v119
	v_add_f32_e32 v112, 1.0, v112
	v_add_f32_e32 v113, 1.0, v113
	v_add_f32_e32 v114, 1.0, v114
	v_add_f32_e32 v115, 1.0, v115
	v_rcp_f32_e32 v116, v116
	v_rcp_f32_e32 v117, v117
	v_rcp_f32_e32 v118, v118
	v_rcp_f32_e32 v119, v119
	v_rcp_f32_e32 v112, v112
	v_rcp_f32_e32 v113, v113
	v_rcp_f32_e32 v114, v114
	v_rcp_f32_e32 v115, v115
	v_mul_f32_e32 v124, v124, v170
	v_mul_f32_e32 v125, v125, v170
	v_mul_f32_e32 v126, v126, v170
	v_mul_f32_e32 v127, v127, v170
	v_mul_f32_e32 v120, v120, v170
	v_mul_f32_e32 v121, v121, v170
	v_mul_f32_e32 v122, v122, v170
	v_mul_f32_e32 v123, v123, v170
	v_mul_f32_e32 v124, v124, v116
	v_mul_f32_e32 v125, v125, v117
	v_mul_f32_e32 v126, v126, v118
	v_mul_f32_e32 v127, v127, v119
	v_mul_f32_e32 v120, v120, v112
	v_mul_f32_e32 v121, v121, v113
	v_mul_f32_e32 v122, v122, v114
	v_mul_f32_e32 v123, v123, v115
	v_cvt_pk_bf16_f32 v116, v124, v125
	v_cvt_pk_bf16_f32 v117, v126, v127
	v_cvt_pk_bf16_f32 v118, v120, v121
	v_cvt_pk_bf16_f32 v119, v122, v123
	global_store_dwordx4 v171, v[116:119], s[10:11]
; __device__ __forceinline__ unsigned cvt_pk_bf16(float lo, float hi) { unsigned r; asm volatile("v_cvt_pk_bf16_f32 %0, %1, %2" : "=v"(r) : "v"(lo), "v"(hi)); return r; }
;     __device__ __forceinline__ void operator()(const f32x4 (&acc)[2][2][4][2], const Unit& u, int wr, int wc, int fr, int fq) const {
;     ...
;             for (int m = 0; m < 4; ++m) { const int row = row0 + ai * HALF + m * 16; const float rs = row_rstd(ssq, row, fr, fq), rs2 = rs * rs, nrl = -1.4426950408889634f * rs;
;                 float o[8];
; #pragma unroll
;                 for (int n = 0; n < 2; ++n) { const f32x4 g = acc[ai][0][m][n], gu = g * acc[ai][1][m][n] * rs2;
; #pragma unroll
;                     for (int j = 0; j < 4; ++j) o[4 * n + j] = gu[j] * __builtin_amdgcn_rcpf(1.0f + __builtin_amdgcn_exp2f(g[j] * nrl)); }
;                 u32x4 w; w.x = cvt_pk_bf16(o[0], o[1]); w.y = cvt_pk_bf16(o[2], o[3]); w.z = cvt_pk_bf16(o[4], o[5]); w.w = cvt_pk_bf16(o[6], o[7]);
;                 *(u32x4*)(ACT + (size_t)row * 5632 + ch0) = w;
	v_add_u32_e32 v179, 0x2c000, v162
	v_mul_f32_e32 v100, v100, v177
	v_mul_f32_e32 v101, v101, v177
	v_mul_f32_e32 v102, v102, v177
	v_mul_f32_e32 v103, v103, v177
	v_mul_f32_e32 v96, v96, v177
	v_mul_f32_e32 v97, v97, v177
	v_mul_f32_e32 v98, v98, v177
	v_mul_f32_e32 v99, v99, v177
	v_exp_f32_e32 v100, v100
	v_exp_f32_e32 v101, v101
	v_exp_f32_e32 v102, v102
	v_exp_f32_e32 v103, v103
	v_exp_f32_e32 v96, v96
	v_exp_f32_e32 v97, v97
	v_exp_f32_e32 v98, v98
	v_exp_f32_e32 v99, v99
	v_add_f32_e32 v100, 1.0, v100
	v_add_f32_e32 v101, 1.0, v101
	v_add_f32_e32 v102, 1.0, v102
	v_add_f32_e32 v103, 1.0, v103
	v_add_f32_e32 v96, 1.0, v96
	v_add_f32_e32 v97, 1.0, v97
	v_add_f32_e32 v98, 1.0, v98
	v_add_f32_e32 v99, 1.0, v99
	v_rcp_f32_e32 v100, v100
	v_rcp_f32_e32 v101, v101
	v_rcp_f32_e32 v102, v102
	v_rcp_f32_e32 v103, v103
	v_rcp_f32_e32 v96, v96
	v_rcp_f32_e32 v97, v97
	v_rcp_f32_e32 v98, v98
	v_rcp_f32_e32 v99, v99
	v_mul_f32_e32 v108, v108, v178
	v_mul_f32_e32 v109, v109, v178
	v_mul_f32_e32 v110, v110, v178
	v_mul_f32_e32 v111, v111, v178
	v_mul_f32_e32 v104, v104, v178
	v_mul_f32_e32 v105, v105, v178
	v_mul_f32_e32 v106, v106, v178
	v_mul_f32_e32 v107, v107, v178
	v_mul_f32_e32 v108, v108, v100
	v_mul_f32_e32 v109, v109, v101
	v_mul_f32_e32 v110, v110, v102
	v_mul_f32_e32 v111, v111, v103
	v_mul_f32_e32 v104, v104, v96
	v_mul_f32_e32 v105, v105, v97
	v_mul_f32_e32 v106, v106, v98
	v_mul_f32_e32 v107, v107, v99
	v_cvt_pk_bf16_f32 v100, v108, v109
	v_cvt_pk_bf16_f32 v101, v110, v111
	v_cvt_pk_bf16_f32 v102, v104, v105
	v_cvt_pk_bf16_f32 v103, v106, v107
	global_store_dwordx4 v179, v[100:103], s[10:11]
	v_add_u32_e32 v187, 0x58000, v162
	v_mul_f32_e32 v84, v84, v185
	v_mul_f32_e32 v85, v85, v185
	v_mul_f32_e32 v86, v86, v185
	v_mul_f32_e32 v87, v87, v185
	v_mul_f32_e32 v80, v80, v185
	v_mul_f32_e32 v81, v81, v185
	v_mul_f32_e32 v82, v82, v185
	v_mul_f32_e32 v83, v83, v185
	v_exp_f32_e32 v84, v84
	v_exp_f32_e32 v85, v85
	v_exp_f32_e32 v86, v86
	v_exp_f32_e32 v87, v87
	v_exp_f32_e32 v80, v80
	v_exp_f32_e32 v81, v81
	v_exp_f32_e32 v82, v82
	v_exp_f32_e32 v83, v83
	v_add_f32_e32 v84, 1.0, v84
	v_add_f32_e32 v85, 1.0, v85
	v_add_f32_e32 v86, 1.0, v86
	v_add_f32_e32 v87, 1.0, v87
	v_add_f32_e32 v80, 1.0, v80
	v_add_f32_e32 v81, 1.0, v81
	v_add_f32_e32 v82, 1.0, v82
	v_add_f32_e32 v83, 1.0, v83
	v_rcp_f32_e32 v84, v84
	v_rcp_f32_e32 v85, v85
	v_rcp_f32_e32 v86, v86
	v_rcp_f32_e32 v87, v87
	v_rcp_f32_e32 v80, v80
	v_rcp_f32_e32 v81, v81
	v_rcp_f32_e32 v82, v82
	v_rcp_f32_e32 v83, v83
	v_mul_f32_e32 v92, v92, v186
	v_mul_f32_e32 v93, v93, v186
	v_mul_f32_e32 v94, v94, v186
	v_mul_f32_e32 v95, v95, v186
	v_mul_f32_e32 v88, v88, v186
	v_mul_f32_e32 v89, v89, v186
	v_mul_f32_e32 v90, v90, v186
	v_mul_f32_e32 v91, v91, v186
	v_mul_f32_e32 v92, v92, v84
	v_mul_f32_e32 v93, v93, v85
	v_mul_f32_e32 v94, v94, v86
	v_mul_f32_e32 v95, v95, v87
	v_mul_f32_e32 v88, v88, v80
	v_mul_f32_e32 v89, v89, v81
	v_mul_f32_e32 v90, v90, v82
	v_mul_f32_e32 v91, v91, v83
	v_cvt_pk_bf16_f32 v84, v92, v93
	v_cvt_pk_bf16_f32 v85, v94, v95
	v_cvt_pk_bf16_f32 v86, v88, v89
	v_cvt_pk_bf16_f32 v87, v90, v91
	global_store_dwordx4 v187, v[84:87], s[10:11]
	v_add_u32_e32 v195, 0x84000, v162
	v_mul_f32_e32 v68, v68, v193
	v_mul_f32_e32 v69, v69, v193
	v_mul_f32_e32 v70, v70, v193
	v_mul_f32_e32 v71, v71, v193
	v_mul_f32_e32 v64, v64, v193
	v_mul_f32_e32 v65, v65, v193
	v_mul_f32_e32 v66, v66, v193
	v_mul_f32_e32 v67, v67, v193
	v_exp_f32_e32 v68, v68
	v_exp_f32_e32 v69, v69
	v_exp_f32_e32 v70, v70
	v_exp_f32_e32 v71, v71
	v_exp_f32_e32 v64, v64
	v_exp_f32_e32 v65, v65
	v_exp_f32_e32 v66, v66
	v_exp_f32_e32 v67, v67
	v_add_f32_e32 v68, 1.0, v68
	v_add_f32_e32 v69, 1.0, v69
	v_add_f32_e32 v70, 1.0, v70
	v_add_f32_e32 v71, 1.0, v71
	v_add_f32_e32 v64, 1.0, v64
	v_add_f32_e32 v65, 1.0, v65
	v_add_f32_e32 v66, 1.0, v66
	v_add_f32_e32 v67, 1.0, v67
	v_rcp_f32_e32 v68, v68
	v_rcp_f32_e32 v69, v69
	v_rcp_f32_e32 v70, v70
	v_rcp_f32_e32 v71, v71
	v_rcp_f32_e32 v64, v64
	v_rcp_f32_e32 v65, v65
	v_rcp_f32_e32 v66, v66
	v_rcp_f32_e32 v67, v67
	v_mul_f32_e32 v76, v76, v194
	v_mul_f32_e32 v77, v77, v194
	v_mul_f32_e32 v78, v78, v194
	v_mul_f32_e32 v79, v79, v194
	v_mul_f32_e32 v72, v72, v194
	v_mul_f32_e32 v73, v73, v194
	v_mul_f32_e32 v74, v74, v194
	v_mul_f32_e32 v75, v75, v194
	v_mul_f32_e32 v76, v76, v68
	v_mul_f32_e32 v77, v77, v69
	v_mul_f32_e32 v78, v78, v70
	v_mul_f32_e32 v79, v79, v71
	v_mul_f32_e32 v72, v72, v64
	v_mul_f32_e32 v73, v73, v65
	v_mul_f32_e32 v74, v74, v66
	v_mul_f32_e32 v75, v75, v67
	v_cvt_pk_bf16_f32 v68, v76, v77
	v_cvt_pk_bf16_f32 v69, v78, v79
	v_cvt_pk_bf16_f32 v70, v72, v73
	v_cvt_pk_bf16_f32 v71, v74, v75
	global_store_dwordx4 v195, v[68:71], s[10:11]
	v_add_u32_e32 v203, 0x160000, v162
	v_mul_f32_e32 v52, v52, v201
	v_mul_f32_e32 v53, v53, v201
	v_mul_f32_e32 v54, v54, v201
	v_mul_f32_e32 v55, v55, v201
	v_mul_f32_e32 v48, v48, v201
	v_mul_f32_e32 v49, v49, v201
	v_mul_f32_e32 v50, v50, v201
	v_mul_f32_e32 v51, v51, v201
	v_exp_f32_e32 v52, v52
	v_exp_f32_e32 v53, v53
	v_exp_f32_e32 v54, v54
	v_exp_f32_e32 v55, v55
	v_exp_f32_e32 v48, v48
	v_exp_f32_e32 v49, v49
	v_exp_f32_e32 v50, v50
	v_exp_f32_e32 v51, v51
	v_add_f32_e32 v52, 1.0, v52
	v_add_f32_e32 v53, 1.0, v53
	v_add_f32_e32 v54, 1.0, v54
	v_add_f32_e32 v55, 1.0, v55
	v_add_f32_e32 v48, 1.0, v48
	v_add_f32_e32 v49, 1.0, v49
	v_add_f32_e32 v50, 1.0, v50
	v_add_f32_e32 v51, 1.0, v51
	v_rcp_f32_e32 v52, v52
	v_rcp_f32_e32 v53, v53
	v_rcp_f32_e32 v54, v54
; __device__ __forceinline__ unsigned cvt_pk_bf16(float lo, float hi) { unsigned r; asm volatile("v_cvt_pk_bf16_f32 %0, %1, %2" : "=v"(r) : "v"(lo), "v"(hi)); return r; }
; #define PG8_BAR __builtin_amdgcn_s_barrier()
; template <class Epi, class Sched, bool ALIGN_EPI = false, bool SP2 = false>
; __device__ __forceinline__ void gemm_phase(PG8_LAS unsigned char* lds, const Gemm g, const Sched& S, const Epi& E) {
;     ...
;         if (!has_next) break;
; #pragma unroll
;         for (int a = 0; a < 2; ++a)
; #pragma unroll
;             for (int b = 0; b < 2; ++b)
; #pragma unroll
;                 for (int m = 0; m < 4; ++m)
; #pragma unroll
;                     for (int n = 0; n < 2; ++n) acc[a][b][m][n] = (f32x4){0.f, 0.f, 0.f, 0.f};
;         cur = nxt; cA = nA; cB = nB; ++ui;
;         if constexpr (ALIGN_EPI) { if (wr == 1) PG8_BAR; }
;     __device__ __forceinline__ void operator()(const f32x4 (&acc)[2][2][4][2], const Unit& u, int wr, int wc, int fr, int fq) const {
;     ...
;             for (int m = 0; m < 4; ++m) { const int row = row0 + ai * HALF + m * 16; const float rs = row_rstd(ssq, row, fr, fq), rs2 = rs * rs, nrl = -1.4426950408889634f * rs;
;                 float o[8];
; #pragma unroll
;                 for (int n = 0; n < 2; ++n) { const f32x4 g = acc[ai][0][m][n], gu = g * acc[ai][1][m][n] * rs2;
; #pragma unroll
;                     for (int j = 0; j < 4; ++j) o[4 * n + j] = gu[j] * __builtin_amdgcn_rcpf(1.0f + __builtin_amdgcn_exp2f(g[j] * nrl)); }
;                 u32x4 w; w.x = cvt_pk_bf16(o[0], o[1]); w.y = cvt_pk_bf16(o[2], o[3]); w.z = cvt_pk_bf16(o[4], o[5]); w.w = cvt_pk_bf16(o[6], o[7]);
;                 *(u32x4*)(ACT + (size_t)row * 5632 + ch0) = w;
	v_rcp_f32_e32 v55, v55
	v_rcp_f32_e32 v48, v48
	v_rcp_f32_e32 v49, v49
	v_rcp_f32_e32 v50, v50
	v_rcp_f32_e32 v51, v51
	v_mul_f32_e32 v60, v60, v202
	v_mul_f32_e32 v61, v61, v202
	v_mul_f32_e32 v62, v62, v202
	v_mul_f32_e32 v63, v63, v202
	v_mul_f32_e32 v56, v56, v202
	v_mul_f32_e32 v57, v57, v202
	v_mul_f32_e32 v58, v58, v202
	v_mul_f32_e32 v59, v59, v202
	v_mul_f32_e32 v60, v60, v52
	v_mul_f32_e32 v61, v61, v53
	v_mul_f32_e32 v62, v62, v54
	v_mul_f32_e32 v63, v63, v55
	v_mul_f32_e32 v56, v56, v48
	v_mul_f32_e32 v57, v57, v49
	v_mul_f32_e32 v58, v58, v50
	v_mul_f32_e32 v59, v59, v51
	v_cvt_pk_bf16_f32 v52, v60, v61
	v_cvt_pk_bf16_f32 v53, v62, v63
	v_cvt_pk_bf16_f32 v54, v56, v57
	v_cvt_pk_bf16_f32 v55, v58, v59
	global_store_dwordx4 v203, v[52:55], s[10:11]
	v_add_u32_e32 v211, 0x18c000, v162
	v_mul_f32_e32 v36, v36, v209
	v_mul_f32_e32 v37, v37, v209
	v_mul_f32_e32 v38, v38, v209
	v_mul_f32_e32 v39, v39, v209
	v_mul_f32_e32 v32, v32, v209
	v_mul_f32_e32 v33, v33, v209
	v_mul_f32_e32 v34, v34, v209
	v_mul_f32_e32 v35, v35, v209
	v_exp_f32_e32 v36, v36
	v_exp_f32_e32 v37, v37
	v_exp_f32_e32 v38, v38
	v_exp_f32_e32 v39, v39
	v_exp_f32_e32 v32, v32
	v_exp_f32_e32 v33, v33
	v_exp_f32_e32 v34, v34
	v_exp_f32_e32 v35, v35
	v_add_f32_e32 v36, 1.0, v36
	v_add_f32_e32 v37, 1.0, v37
	v_add_f32_e32 v38, 1.0, v38
	v_add_f32_e32 v39, 1.0, v39
	v_add_f32_e32 v32, 1.0, v32
	v_add_f32_e32 v33, 1.0, v33
	v_add_f32_e32 v34, 1.0, v34
	v_add_f32_e32 v35, 1.0, v35
	v_rcp_f32_e32 v36, v36
	v_rcp_f32_e32 v37, v37
	v_rcp_f32_e32 v38, v38
	v_rcp_f32_e32 v39, v39
	v_rcp_f32_e32 v32, v32
	v_rcp_f32_e32 v33, v33
	v_rcp_f32_e32 v34, v34
	v_rcp_f32_e32 v35, v35
	v_mul_f32_e32 v44, v44, v210
	v_mul_f32_e32 v45, v45, v210
	v_mul_f32_e32 v46, v46, v210
	v_mul_f32_e32 v47, v47, v210
	v_mul_f32_e32 v40, v40, v210
	v_mul_f32_e32 v41, v41, v210
	v_mul_f32_e32 v42, v42, v210
	v_mul_f32_e32 v43, v43, v210
	v_mul_f32_e32 v44, v44, v36
	v_mul_f32_e32 v45, v45, v37
	v_mul_f32_e32 v46, v46, v38
	v_mul_f32_e32 v47, v47, v39
	v_mul_f32_e32 v40, v40, v32
	v_mul_f32_e32 v41, v41, v33
	v_mul_f32_e32 v42, v42, v34
	v_mul_f32_e32 v43, v43, v35
	v_cvt_pk_bf16_f32 v36, v44, v45
	v_cvt_pk_bf16_f32 v37, v46, v47
	v_cvt_pk_bf16_f32 v38, v40, v41
	v_cvt_pk_bf16_f32 v39, v42, v43
	global_store_dwordx4 v211, v[36:39], s[10:11]
	v_add_u32_e32 v219, 0x1b8000, v162
	v_mul_f32_e32 v20, v20, v217
	v_mul_f32_e32 v21, v21, v217
	v_mul_f32_e32 v22, v22, v217
	v_mul_f32_e32 v23, v23, v217
	v_mul_f32_e32 v16, v16, v217
	v_mul_f32_e32 v17, v17, v217
	v_mul_f32_e32 v18, v18, v217
	v_mul_f32_e32 v19, v19, v217
	v_exp_f32_e32 v20, v20
	v_exp_f32_e32 v21, v21
	v_exp_f32_e32 v22, v22
	v_exp_f32_e32 v23, v23
	v_exp_f32_e32 v16, v16
	v_exp_f32_e32 v17, v17
	v_exp_f32_e32 v18, v18
	v_exp_f32_e32 v19, v19
	v_add_f32_e32 v20, 1.0, v20
	v_add_f32_e32 v21, 1.0, v21
	v_add_f32_e32 v22, 1.0, v22
	v_add_f32_e32 v23, 1.0, v23
	v_add_f32_e32 v16, 1.0, v16
	v_add_f32_e32 v17, 1.0, v17
	v_add_f32_e32 v18, 1.0, v18
	v_add_f32_e32 v19, 1.0, v19
	v_rcp_f32_e32 v20, v20
	v_rcp_f32_e32 v21, v21
	v_rcp_f32_e32 v22, v22
	v_rcp_f32_e32 v23, v23
	v_rcp_f32_e32 v16, v16
	v_rcp_f32_e32 v17, v17
	v_rcp_f32_e32 v18, v18
	v_rcp_f32_e32 v19, v19
	v_mul_f32_e32 v28, v28, v218
	v_mul_f32_e32 v29, v29, v218
	v_mul_f32_e32 v30, v30, v218
	v_mul_f32_e32 v31, v31, v218
	v_mul_f32_e32 v24, v24, v218
	v_mul_f32_e32 v25, v25, v218
	v_mul_f32_e32 v26, v26, v218
	v_mul_f32_e32 v27, v27, v218
	v_mul_f32_e32 v28, v28, v20
	v_mul_f32_e32 v29, v29, v21
	v_mul_f32_e32 v30, v30, v22
	v_mul_f32_e32 v31, v31, v23
	v_mul_f32_e32 v24, v24, v16
	v_mul_f32_e32 v25, v25, v17
	v_mul_f32_e32 v26, v26, v18
	v_mul_f32_e32 v27, v27, v19
	v_cvt_pk_bf16_f32 v20, v28, v29
	v_cvt_pk_bf16_f32 v21, v30, v31
	v_cvt_pk_bf16_f32 v22, v24, v25
	v_cvt_pk_bf16_f32 v23, v26, v27
	global_store_dwordx4 v219, v[20:23], s[10:11]
	v_add_u32_e32 v227, 0x1e4000, v162
	v_mul_f32_e32 v8, v8, v225
	v_mul_f32_e32 v9, v9, v225
	v_mul_f32_e32 v10, v10, v225
	v_mul_f32_e32 v11, v11, v225
	v_mul_f32_e32 v4, v4, v225
	v_mul_f32_e32 v5, v5, v225
	v_mul_f32_e32 v6, v6, v225
	v_mul_f32_e32 v7, v7, v225
	v_exp_f32_e32 v8, v8
	v_exp_f32_e32 v9, v9
	v_exp_f32_e32 v10, v10
	v_exp_f32_e32 v11, v11
	v_exp_f32_e32 v4, v4
	v_exp_f32_e32 v5, v5
	v_exp_f32_e32 v6, v6
	v_exp_f32_e32 v7, v7
	v_add_f32_e32 v8, 1.0, v8
	v_add_f32_e32 v9, 1.0, v9
	v_add_f32_e32 v10, 1.0, v10
	v_add_f32_e32 v11, 1.0, v11
	v_add_f32_e32 v4, 1.0, v4
	v_add_f32_e32 v5, 1.0, v5
	v_add_f32_e32 v6, 1.0, v6
	v_add_f32_e32 v7, 1.0, v7
	v_rcp_f32_e32 v8, v8
	v_rcp_f32_e32 v9, v9
	v_rcp_f32_e32 v10, v10
	v_rcp_f32_e32 v11, v11
	v_rcp_f32_e32 v4, v4
	v_rcp_f32_e32 v5, v5
	v_rcp_f32_e32 v6, v6
	v_rcp_f32_e32 v7, v7
	v_mul_f32_e32 v12, v12, v226
	v_mul_f32_e32 v13, v13, v226
	v_mul_f32_e32 v14, v14, v226
	v_mul_f32_e32 v15, v15, v226
	v_mul_f32_e32 v0, v0, v226
	v_mul_f32_e32 v1, v1, v226
	v_mul_f32_e32 v2, v2, v226
	v_mul_f32_e32 v3, v3, v226
	v_mul_f32_e32 v12, v12, v8
	v_mul_f32_e32 v13, v13, v9
	v_mul_f32_e32 v14, v14, v10
	v_mul_f32_e32 v15, v15, v11
	v_mul_f32_e32 v0, v0, v4
	v_mul_f32_e32 v1, v1, v5
	v_mul_f32_e32 v2, v2, v6
	v_mul_f32_e32 v3, v3, v7
	v_cvt_pk_bf16_f32 v8, v12, v13
	v_cvt_pk_bf16_f32 v9, v14, v15
	v_cvt_pk_bf16_f32 v10, v0, v1
	v_cvt_pk_bf16_f32 v11, v2, v3
	global_store_dwordx4 v227, v[8:11], s[10:11]
	s_andn2_b64 vcc, exec, s[8:9]
	s_mov_b64 s[8:9], -1
	s_cbranch_vccnz .LBB0_732
	s_and_b64 vcc, exec, s[64:65]
	s_cbranch_vccnz .LBB0_731
	s_barrier
	s_branch .LBB0_731

; #define PG8_STAGE(bufoff, gbase, voff) do { _Pragma("unroll") for (int _i = 0; _i < 2; ++_i) \
;         __builtin_amdgcn_global_load_lds((const unsigned*)((const char*)(gbase) + (voff)[_i]), (PG8_LAS unsigned*)(lds + (bufoff) + ldsw + _i * 8192), 16, 0, 0); } while (0)
; #define PG8_LDA(dst, b, h) do { _Pragma("unroll") for (int m = 0; m < 4; ++m) _Pragma("unroll") for (int k = 0; k < 2; ++k) dst[m][k] = *(const PG8_LAS bf16x8*)(lds + PG8_SA(b, h) + aoff + m * 2048 + k * 1024); } while (0)
; #define PG8_LDB(dst, b, h) do { _Pragma("unroll") for (int n = 0; n < 2; ++n) _Pragma("unroll") for (int k = 0; k < 2; ++k) dst[n][k] = *(const PG8_LAS bf16x8*)(lds + PG8_SB(b, h) + boff + n * 2048 + k * 1024); } while (0)
; #define PG8_MMA(ai, bj, At, Bt) do { __builtin_amdgcn_s_setprio(1); _Pragma("unroll") for (int m = 0; m < 4; ++m) _Pragma("unroll") for (int n = 0; n < 2; ++n) _Pragma("unroll") for (int k = 0; k < 2; ++k) \
;         acc[ai][bj][m][n] = __builtin_amdgcn_mfma_f32_16x16x32_bf16(Bt[n][k], At[m][k], acc[ai][bj][m][n], 0, 0, 0); __builtin_amdgcn_s_setprio(0); } while (0)
; #define PG8_WAIT_V(n) asm volatile("s_waitcnt vmcnt(" #n ")" ::: "memory")
; #define PG8_WAIT_L(n) asm volatile("s_waitcnt lgkmcnt(" #n ")" ::: "memory")
; #define PG8_BAR __builtin_amdgcn_s_barrier()
; #define PG8_SCHED __builtin_amdgcn_sched_barrier(0)
; template <class Epi, class Sched, bool ALIGN_EPI = false, bool SP2 = false>
; __device__ __forceinline__ void gemm_phase(PG8_LAS unsigned char* lds, const Gemm g, const Sched& S, const Epi& E) {
;     ...
;             PG8_LDB(B0, 0, 0); PG8_LDB(B1, 0, 1); PG8_SCHED; PG8_LDA(At, 0, 0); PG8_STAGE(PG8_SA(1, 1), a1 + hstepA, voffA);
;             PG8_WAIT_V(8); PG8_WAIT_L(0); PG8_BAR; PG8_MMA(0, 0, At, B0); PG8_MMA(0, 1, At, B1); PG8_BAR; PG8_SCHED;
;     ...
; #pragma unroll
;         for (int a = 0; a < 2; ++a)
; #pragma unroll
;             for (int b = 0; b < 2; ++b)
; #pragma unroll
;                 for (int m = 0; m < 4; ++m)
; #pragma unroll
;                     for (int n = 0; n < 2; ++n) acc[a][b][m][n] = (f32x4){0.f, 0.f, 0.f, 0.f};
;         cur = nxt; cA = nA; cB = nB; ++ui;
.LBB0_1286:
	s_ashr_i32 s19, s18, 31
	s_lshl_b64 s[4:5], s[18:19], 20
	s_add_u32 s20, s0, s4
	s_addc_u32 s21, s1, s5
	s_and_b64 s[4:5], s[8:9], exec
	s_cselect_b32 s19, s21, s29
	s_cselect_b32 s54, s20, s28
	s_ashr_i32 s17, s16, 31
	s_lshl_b64 s[4:5], s[16:17], 20
	s_add_u32 s22, s3, s4
	s_addc_u32 s23, s24, s5
	s_and_b64 s[4:5], s[8:9], exec
	s_cselect_b32 s17, s23, s31
	s_cselect_b32 s55, s22, s30
	s_add_u32 s28, s28, 0x80080
	s_addc_u32 s29, s29, 0
	s_add_u32 s56, s30, 0x100
	v_mov_b32_e32 v0, 0
	s_addc_u32 s57, s31, 0
	s_mov_b32 s58, -2
	v_mov_b32_e32 v1, v0
	v_mov_b32_e32 v2, v0
	v_mov_b32_e32 v3, v0
	v_mov_b32_e32 v12, v0
	v_mov_b32_e32 v13, v0
	v_mov_b32_e32 v14, v0
	v_mov_b32_e32 v15, v0
	v_mov_b32_e32 v24, v0
	v_mov_b32_e32 v25, v0
	v_mov_b32_e32 v26, v0
	v_mov_b32_e32 v27, v0
	v_mov_b32_e32 v28, v0
	v_mov_b32_e32 v29, v0
	v_mov_b32_e32 v30, v0
	v_mov_b32_e32 v31, v0
	v_mov_b32_e32 v40, v0
	v_mov_b32_e32 v41, v0
	v_mov_b32_e32 v42, v0
	v_mov_b32_e32 v43, v0
	v_mov_b32_e32 v44, v0
	v_mov_b32_e32 v45, v0
	v_mov_b32_e32 v46, v0
	v_mov_b32_e32 v47, v0
	v_mov_b32_e32 v56, v0
	v_mov_b32_e32 v57, v0
	v_mov_b32_e32 v58, v0
	v_mov_b32_e32 v59, v0
	v_mov_b32_e32 v60, v0
	v_mov_b32_e32 v61, v0
	v_mov_b32_e32 v62, v0
	v_mov_b32_e32 v63, v0
	v_mov_b32_e32 v4, v0
	v_mov_b32_e32 v5, v0
	v_mov_b32_e32 v6, v0
	v_mov_b32_e32 v7, v0
	v_mov_b32_e32 v8, v0
	v_mov_b32_e32 v9, v0
	v_mov_b32_e32 v10, v0
	v_mov_b32_e32 v11, v0
	v_mov_b32_e32 v16, v0
	v_mov_b32_e32 v17, v0
	v_mov_b32_e32 v18, v0
	v_mov_b32_e32 v19, v0
	v_mov_b32_e32 v20, v0
	v_mov_b32_e32 v21, v0
	v_mov_b32_e32 v22, v0
	v_mov_b32_e32 v23, v0
	v_mov_b32_e32 v32, v0
	v_mov_b32_e32 v33, v0
	v_mov_b32_e32 v34, v0
	v_mov_b32_e32 v35, v0
	v_mov_b32_e32 v36, v0
	v_mov_b32_e32 v37, v0
	v_mov_b32_e32 v38, v0
	v_mov_b32_e32 v39, v0
	v_mov_b32_e32 v48, v0
	v_mov_b32_e32 v49, v0
	v_mov_b32_e32 v50, v0
	v_mov_b32_e32 v51, v0
	v_mov_b32_e32 v52, v0
	v_mov_b32_e32 v53, v0
	v_mov_b32_e32 v54, v0
	v_mov_b32_e32 v55, v0
	v_mov_b32_e32 v72, v0
	v_mov_b32_e32 v73, v0
	v_mov_b32_e32 v74, v0
	v_mov_b32_e32 v75, v0
	v_mov_b32_e32 v76, v0
	v_mov_b32_e32 v77, v0
	v_mov_b32_e32 v78, v0
	v_mov_b32_e32 v79, v0
	v_mov_b32_e32 v88, v0
	v_mov_b32_e32 v89, v0
	v_mov_b32_e32 v90, v0
	v_mov_b32_e32 v91, v0
	v_mov_b32_e32 v92, v0
	v_mov_b32_e32 v93, v0
	v_mov_b32_e32 v94, v0
	v_mov_b32_e32 v95, v0
	v_mov_b32_e32 v104, v0
	v_mov_b32_e32 v105, v0
	v_mov_b32_e32 v106, v0
	v_mov_b32_e32 v107, v0
	v_mov_b32_e32 v108, v0
	v_mov_b32_e32 v109, v0
	v_mov_b32_e32 v110, v0
	v_mov_b32_e32 v111, v0
	v_mov_b32_e32 v120, v0
	v_mov_b32_e32 v121, v0
	v_mov_b32_e32 v122, v0
	v_mov_b32_e32 v123, v0
	v_mov_b32_e32 v124, v0
	v_mov_b32_e32 v125, v0
	v_mov_b32_e32 v126, v0
	v_mov_b32_e32 v127, v0
	v_mov_b32_e32 v64, v0
	v_mov_b32_e32 v65, v0
	v_mov_b32_e32 v66, v0
	v_mov_b32_e32 v67, v0
	v_mov_b32_e32 v68, v0
	v_mov_b32_e32 v69, v0
	v_mov_b32_e32 v70, v0
	v_mov_b32_e32 v71, v0
	v_mov_b32_e32 v80, v0
	v_mov_b32_e32 v81, v0
	v_mov_b32_e32 v82, v0
	v_mov_b32_e32 v83, v0
	v_mov_b32_e32 v84, v0
	v_mov_b32_e32 v85, v0
	v_mov_b32_e32 v86, v0
	v_mov_b32_e32 v87, v0
	v_mov_b32_e32 v96, v0
	v_mov_b32_e32 v97, v0
	v_mov_b32_e32 v98, v0
	v_mov_b32_e32 v99, v0
	v_mov_b32_e32 v100, v0
	v_mov_b32_e32 v101, v0
	v_mov_b32_e32 v102, v0
	v_mov_b32_e32 v103, v0
	v_mov_b32_e32 v112, v0
	v_mov_b32_e32 v113, v0
	v_mov_b32_e32 v114, v0
	v_mov_b32_e32 v115, v0
	v_mov_b32_e32 v116, v0
	v_mov_b32_e32 v117, v0
	v_mov_b32_e32 v118, v0
	v_mov_b32_e32 v119, v0
.LBB0_1287:
	ds_read_b128 v[144:147], v149
	ds_read_b128 v[154:157], v149 offset:1024
	ds_read_b128 v[158:161], v149 offset:2048
	ds_read_b128 v[162:165], v149 offset:3072
	ds_read_b128 v[168:171], v150
	ds_read_b128 v[172:175], v150 offset:1024
	ds_read_b128 v[176:179], v150 offset:2048
	ds_read_b128 v[180:183], v150 offset:3072
	s_add_u32 s4, s28, 0xfff80080
	s_addc_u32 s5, s29, -1
	s_cmp_eq_u32 s58, 28
	s_cselect_b32 s35, s19, s5
	s_cselect_b32 s34, s54, s4
	s_cselect_b32 s31, s17, s57
	s_cselect_b32 s30, s55, s56
	v_lshl_add_u64 v[216:217], s[28:29], 0, v[136:137]
	s_add_i32 m0, s27, 0xc000
	ds_read_b128 v[184:187], v151
	ds_read_b128 v[188:191], v151 offset:1024
	ds_read_b128 v[192:195], v151 offset:2048
	ds_read_b128 v[196:199], v151 offset:3072
	ds_read_b128 v[200:203], v151 offset:4096
	ds_read_b128 v[204:207], v151 offset:5120
	ds_read_b128 v[208:211], v151 offset:6144
	ds_read_b128 v[212:215], v151 offset:7168
	global_load_lds_dwordx4 v[216:217], off
	v_lshl_add_u64 v[216:217], s[28:29], 0, v[138:139]
	s_add_i32 m0, s27, 0xe000
	s_nop 0
	global_load_lds_dwordx4 v[216:217], off
	s_waitcnt vmcnt(8)
	s_waitcnt lgkmcnt(0)
	s_barrier
; #define PG8_STAGE(bufoff, gbase, voff) do { _Pragma("unroll") for (int _i = 0; _i < 2; ++_i) \
;         __builtin_amdgcn_global_load_lds((const unsigned*)((const char*)(gbase) + (voff)[_i]), (PG8_LAS unsigned*)(lds + (bufoff) + ldsw + _i * 8192), 16, 0, 0); } while (0)
; #define PG8_LDA(dst, b, h) do { _Pragma("unroll") for (int m = 0; m < 4; ++m) _Pragma("unroll") for (int k = 0; k < 2; ++k) dst[m][k] = *(const PG8_LAS bf16x8*)(lds + PG8_SA(b, h) + aoff + m * 2048 + k * 1024); } while (0)
; #define PG8_MMA(ai, bj, At, Bt) do { __builtin_amdgcn_s_setprio(1); _Pragma("unroll") for (int m = 0; m < 4; ++m) _Pragma("unroll") for (int n = 0; n < 2; ++n) _Pragma("unroll") for (int k = 0; k < 2; ++k) \
;         acc[ai][bj][m][n] = __builtin_amdgcn_mfma_f32_16x16x32_bf16(Bt[n][k], At[m][k], acc[ai][bj][m][n], 0, 0, 0); __builtin_amdgcn_s_setprio(0); } while (0)
; #define PG8_WAIT_V(n) asm volatile("s_waitcnt vmcnt(" #n ")" ::: "memory")
; #define PG8_WAIT_L(n) asm volatile("s_waitcnt lgkmcnt(" #n ")" ::: "memory")
; #define PG8_BAR __builtin_amdgcn_s_barrier()
; #define PG8_SCHED __builtin_amdgcn_sched_barrier(0)
; template <class Epi, class Sched, bool ALIGN_EPI = false, bool SP2 = false>
; __device__ __forceinline__ void gemm_phase(PG8_LAS unsigned char* lds, const Gemm g, const Sched& S, const Epi& E) {
;     ...
;             PG8_WAIT_V(8); PG8_WAIT_L(0); PG8_BAR; PG8_MMA(0, 0, At, B0); PG8_MMA(0, 1, At, B1); PG8_BAR; PG8_SCHED;
;             PG8_LDA(At, 0, 1); PG8_STAGE(PG8_SB(0, 0), b2, voffB); PG8_STAGE(PG8_SB(0, 1), b2 + hstepB, voffB); PG8_STAGE(PG8_SA(0, 0), a2, voffA);
;             PG8_WAIT_V(8); PG8_WAIT_L(0); PG8_BAR; PG8_MMA(1, 0, At, B0); PG8_MMA(1, 1, At, B1); PG8_BAR; PG8_SCHED;
	s_setprio 1
	s_waitcnt lgkmcnt(0)
	v_mfma_f32_16x16x32_bf16 v[116:119], v[144:147], v[184:187], v[116:119]
	v_mfma_f32_16x16x32_bf16 v[112:115], v[158:161], v[184:187], v[112:115]
	v_mfma_f32_16x16x32_bf16 v[100:103], v[144:147], v[192:195], v[100:103]
	v_mfma_f32_16x16x32_bf16 v[96:99], v[158:161], v[192:195], v[96:99]
	v_mfma_f32_16x16x32_bf16 v[84:87], v[144:147], v[200:203], v[84:87]
	v_mfma_f32_16x16x32_bf16 v[80:83], v[158:161], v[200:203], v[80:83]
	v_mfma_f32_16x16x32_bf16 v[68:71], v[144:147], v[208:211], v[68:71]
	v_mfma_f32_16x16x32_bf16 v[64:67], v[158:161], v[208:211], v[64:67]
	v_mfma_f32_16x16x32_bf16 v[116:119], v[154:157], v[188:191], v[116:119]
	v_mfma_f32_16x16x32_bf16 v[112:115], v[162:165], v[188:191], v[112:115]
	v_mfma_f32_16x16x32_bf16 v[100:103], v[154:157], v[196:199], v[100:103]
	v_mfma_f32_16x16x32_bf16 v[96:99], v[162:165], v[196:199], v[96:99]
	v_mfma_f32_16x16x32_bf16 v[84:87], v[154:157], v[204:207], v[84:87]
	v_mfma_f32_16x16x32_bf16 v[80:83], v[162:165], v[204:207], v[80:83]
	v_mfma_f32_16x16x32_bf16 v[68:71], v[154:157], v[212:215], v[68:71]
	v_mfma_f32_16x16x32_bf16 v[64:67], v[162:165], v[212:215], v[64:67]
	s_setprio 0
	s_setprio 1
	v_mfma_f32_16x16x32_bf16 v[124:127], v[168:171], v[184:187], v[124:127]
	v_mfma_f32_16x16x32_bf16 v[120:123], v[176:179], v[184:187], v[120:123]
	v_mfma_f32_16x16x32_bf16 v[108:111], v[168:171], v[192:195], v[108:111]
	v_mfma_f32_16x16x32_bf16 v[104:107], v[176:179], v[192:195], v[104:107]
	v_mfma_f32_16x16x32_bf16 v[92:95], v[168:171], v[200:203], v[92:95]
	v_mfma_f32_16x16x32_bf16 v[88:91], v[176:179], v[200:203], v[88:91]
	v_mfma_f32_16x16x32_bf16 v[76:79], v[168:171], v[208:211], v[76:79]
	v_mfma_f32_16x16x32_bf16 v[72:75], v[176:179], v[208:211], v[72:75]
	v_mfma_f32_16x16x32_bf16 v[124:127], v[172:175], v[188:191], v[124:127]
	v_mfma_f32_16x16x32_bf16 v[120:123], v[180:183], v[188:191], v[120:123]
	v_mfma_f32_16x16x32_bf16 v[108:111], v[172:175], v[196:199], v[108:111]
	v_mfma_f32_16x16x32_bf16 v[104:107], v[180:183], v[196:199], v[104:107]
	v_mfma_f32_16x16x32_bf16 v[92:95], v[172:175], v[204:207], v[92:95]
	v_mfma_f32_16x16x32_bf16 v[88:91], v[180:183], v[204:207], v[88:91]
	v_mfma_f32_16x16x32_bf16 v[76:79], v[172:175], v[212:215], v[76:79]
	v_mfma_f32_16x16x32_bf16 v[72:75], v[180:183], v[212:215], v[72:75]
	s_setprio 0
	s_barrier
	s_add_i32 s4, s41, s47
	v_lshl_add_u64 v[216:217], s[30:31], 0, v[132:133]
	s_mov_b32 m0, s4
	ds_read_b128 v[184:187], v151 offset:16384
	ds_read_b128 v[188:191], v151 offset:17408
	ds_read_b128 v[192:195], v151 offset:18432
	ds_read_b128 v[196:199], v151 offset:19456
	ds_read_b128 v[200:203], v151 offset:20480
	ds_read_b128 v[204:207], v151 offset:21504
	ds_read_b128 v[208:211], v151 offset:22528
	ds_read_b128 v[212:215], v151 offset:23552
	global_load_lds_dwordx4 v[216:217], off
	s_add_i32 m0, s4, 0x2000
	s_add_u32 s4, s30, 0x80000
	v_lshl_add_u64 v[218:219], s[30:31], 0, v[128:129]
	s_addc_u32 s5, s31, 0
	s_add_i32 s59, s44, s47
	global_load_lds_dwordx4 v[218:219], off
	v_lshl_add_u64 v[220:221], s[4:5], 0, v[132:133]
	s_mov_b32 m0, s59
	v_lshl_add_u64 v[222:223], s[34:35], 0, v[130:131]
	global_load_lds_dwordx4 v[220:221], off
	v_lshl_add_u64 v[220:221], s[4:5], 0, v[128:129]
	s_add_i32 m0, s59, 0x2000
	s_nop 0
	global_load_lds_dwordx4 v[220:221], off
	v_lshl_add_u64 v[220:221], s[34:35], 0, v[134:135]
	s_mov_b32 m0, s27
	s_nop 0
	global_load_lds_dwordx4 v[220:221], off
	s_mov_b32 m0, s33
	s_nop 0
	global_load_lds_dwordx4 v[222:223], off
	s_waitcnt vmcnt(8)
	s_waitcnt lgkmcnt(0)
	s_barrier
	s_setprio 1
	s_waitcnt lgkmcnt(0)
	v_mfma_f32_16x16x32_bf16 v[52:55], v[144:147], v[184:187], v[52:55]
	v_mfma_f32_16x16x32_bf16 v[48:51], v[158:161], v[184:187], v[48:51]
	v_mfma_f32_16x16x32_bf16 v[36:39], v[144:147], v[192:195], v[36:39]
	v_mfma_f32_16x16x32_bf16 v[32:35], v[158:161], v[192:195], v[32:35]
	v_mfma_f32_16x16x32_bf16 v[20:23], v[144:147], v[200:203], v[20:23]
	v_mfma_f32_16x16x32_bf16 v[16:19], v[158:161], v[200:203], v[16:19]
	v_mfma_f32_16x16x32_bf16 v[8:11], v[144:147], v[208:211], v[8:11]
	v_mfma_f32_16x16x32_bf16 v[4:7], v[158:161], v[208:211], v[4:7]
	v_mfma_f32_16x16x32_bf16 v[52:55], v[154:157], v[188:191], v[52:55]
	v_mfma_f32_16x16x32_bf16 v[48:51], v[162:165], v[188:191], v[48:51]
	v_mfma_f32_16x16x32_bf16 v[36:39], v[154:157], v[196:199], v[36:39]
	v_mfma_f32_16x16x32_bf16 v[32:35], v[162:165], v[196:199], v[32:35]
	v_mfma_f32_16x16x32_bf16 v[20:23], v[154:157], v[204:207], v[20:23]
	v_mfma_f32_16x16x32_bf16 v[16:19], v[162:165], v[204:207], v[16:19]
	v_mfma_f32_16x16x32_bf16 v[8:11], v[154:157], v[212:215], v[8:11]
	v_mfma_f32_16x16x32_bf16 v[4:7], v[162:165], v[212:215], v[4:7]
	s_setprio 0
	s_setprio 1
	v_mfma_f32_16x16x32_bf16 v[60:63], v[168:171], v[184:187], v[60:63]
	v_mfma_f32_16x16x32_bf16 v[56:59], v[176:179], v[184:187], v[56:59]
	v_mfma_f32_16x16x32_bf16 v[44:47], v[168:171], v[192:195], v[44:47]
	v_mfma_f32_16x16x32_bf16 v[40:43], v[176:179], v[192:195], v[40:43]
	v_mfma_f32_16x16x32_bf16 v[28:31], v[168:171], v[200:203], v[28:31]
	v_mfma_f32_16x16x32_bf16 v[24:27], v[176:179], v[200:203], v[24:27]
	v_mfma_f32_16x16x32_bf16 v[12:15], v[168:171], v[208:211], v[12:15]
	v_mfma_f32_16x16x32_bf16 v[0:3], v[176:179], v[208:211], v[0:3]
	v_mfma_f32_16x16x32_bf16 v[60:63], v[172:175], v[188:191], v[60:63]
	v_mfma_f32_16x16x32_bf16 v[56:59], v[180:183], v[188:191], v[56:59]
	v_mfma_f32_16x16x32_bf16 v[44:47], v[172:175], v[196:199], v[44:47]
	v_mfma_f32_16x16x32_bf16 v[40:43], v[180:183], v[196:199], v[40:43]
	v_mfma_f32_16x16x32_bf16 v[28:31], v[172:175], v[204:207], v[28:31]
	v_mfma_f32_16x16x32_bf16 v[24:27], v[180:183], v[204:207], v[24:27]
	v_mfma_f32_16x16x32_bf16 v[12:15], v[172:175], v[212:215], v[12:15]
	v_mfma_f32_16x16x32_bf16 v[0:3], v[180:183], v[212:215], v[0:3]
	s_setprio 0
	s_barrier
; #define PG8_STAGE(bufoff, gbase, voff) do { _Pragma("unroll") for (int _i = 0; _i < 2; ++_i) \
;         __builtin_amdgcn_global_load_lds((const unsigned*)((const char*)(gbase) + (voff)[_i]), (PG8_LAS unsigned*)(lds + (bufoff) + ldsw + _i * 8192), 16, 0, 0); } while (0)
; #define PG8_LDA(dst, b, h) do { _Pragma("unroll") for (int m = 0; m < 4; ++m) _Pragma("unroll") for (int k = 0; k < 2; ++k) dst[m][k] = *(const PG8_LAS bf16x8*)(lds + PG8_SA(b, h) + aoff + m * 2048 + k * 1024); } while (0)
; #define PG8_LDB(dst, b, h) do { _Pragma("unroll") for (int n = 0; n < 2; ++n) _Pragma("unroll") for (int k = 0; k < 2; ++k) dst[n][k] = *(const PG8_LAS bf16x8*)(lds + PG8_SB(b, h) + boff + n * 2048 + k * 1024); } while (0)
; #define PG8_MMA(ai, bj, At, Bt) do { __builtin_amdgcn_s_setprio(1); _Pragma("unroll") for (int m = 0; m < 4; ++m) _Pragma("unroll") for (int n = 0; n < 2; ++n) _Pragma("unroll") for (int k = 0; k < 2; ++k) \
;         acc[ai][bj][m][n] = __builtin_amdgcn_mfma_f32_16x16x32_bf16(Bt[n][k], At[m][k], acc[ai][bj][m][n], 0, 0, 0); __builtin_amdgcn_s_setprio(0); } while (0)
; #define PG8_WAIT_V(n) asm volatile("s_waitcnt vmcnt(" #n ")" ::: "memory")
; #define PG8_WAIT_L(n) asm volatile("s_waitcnt lgkmcnt(" #n ")" ::: "memory")
; #define PG8_BAR __builtin_amdgcn_s_barrier()
; #define PG8_SCHED __builtin_amdgcn_sched_barrier(0)
; template <class Epi, class Sched, bool ALIGN_EPI = false, bool SP2 = false>
; __device__ __forceinline__ void gemm_phase(PG8_LAS unsigned char* lds, const Gemm g, const Sched& S, const Epi& E) {
;     ...
;             PG8_LDB(B0, 1, 0); PG8_LDB(B1, 1, 1); PG8_SCHED; PG8_LDA(At, 1, 0); PG8_STAGE(PG8_SA(0, 1), a2 + hstepA, voffA);
;             PG8_WAIT_V(8); PG8_WAIT_L(0); PG8_BAR; PG8_MMA(0, 0, At, B0); PG8_MMA(0, 1, At, B1); PG8_BAR; PG8_SCHED;
;             PG8_LDA(At, 1, 1); PG8_STAGE(PG8_SB(1, 0), b3, voffB); PG8_STAGE(PG8_SB(1, 1), b3 + hstepB, voffB); PG8_STAGE(PG8_SA(1, 0), a3, voffA);
	s_add_i32 s59, 0, 0x18000
	v_add_u32_e32 v153, s59, v148
	s_add_i32 s60, 0, 0x1c000
	ds_read_b128 v[144:147], v153
	ds_read_b128 v[154:157], v153 offset:1024
	ds_read_b128 v[158:161], v153 offset:2048
	ds_read_b128 v[162:165], v153 offset:3072
	v_add_u32_e32 v153, s60, v148
	ds_read_b128 v[168:171], v153
	ds_read_b128 v[172:175], v153 offset:1024
	ds_read_b128 v[176:179], v153 offset:2048
	ds_read_b128 v[180:183], v153 offset:3072
	s_add_u32 s4, s34, 0x80000
	s_addc_u32 s5, s35, 0
	s_mov_b32 m0, s36
	v_lshl_add_u64 v[224:225], s[4:5], 0, v[134:135]
	ds_read_b128 v[184:187], v151 offset:32768
	ds_read_b128 v[188:191], v151 offset:33792
	ds_read_b128 v[192:195], v151 offset:34816
	ds_read_b128 v[196:199], v151 offset:35840
	ds_read_b128 v[200:203], v151 offset:36864
	ds_read_b128 v[204:207], v151 offset:37888
	ds_read_b128 v[208:211], v151 offset:38912
	ds_read_b128 v[212:215], v151 offset:39936
	global_load_lds_dwordx4 v[224:225], off
	v_lshl_add_u64 v[224:225], s[4:5], 0, v[130:131]
	s_mov_b32 m0, s37
	s_nop 0
	global_load_lds_dwordx4 v[224:225], off
	s_waitcnt vmcnt(8)
	s_waitcnt lgkmcnt(0)
	s_barrier
	s_setprio 1
	s_waitcnt lgkmcnt(0)
	v_mfma_f32_16x16x32_bf16 v[116:119], v[144:147], v[184:187], v[116:119]
	v_mfma_f32_16x16x32_bf16 v[112:115], v[158:161], v[184:187], v[112:115]
	v_mfma_f32_16x16x32_bf16 v[100:103], v[144:147], v[192:195], v[100:103]
	v_mfma_f32_16x16x32_bf16 v[96:99], v[158:161], v[192:195], v[96:99]
	v_mfma_f32_16x16x32_bf16 v[84:87], v[144:147], v[200:203], v[84:87]
	v_mfma_f32_16x16x32_bf16 v[80:83], v[158:161], v[200:203], v[80:83]
	v_mfma_f32_16x16x32_bf16 v[68:71], v[144:147], v[208:211], v[68:71]
	v_mfma_f32_16x16x32_bf16 v[64:67], v[158:161], v[208:211], v[64:67]
	v_mfma_f32_16x16x32_bf16 v[116:119], v[154:157], v[188:191], v[116:119]
	v_mfma_f32_16x16x32_bf16 v[112:115], v[162:165], v[188:191], v[112:115]
	v_mfma_f32_16x16x32_bf16 v[100:103], v[154:157], v[196:199], v[100:103]
	v_mfma_f32_16x16x32_bf16 v[96:99], v[162:165], v[196:199], v[96:99]
	v_mfma_f32_16x16x32_bf16 v[84:87], v[154:157], v[204:207], v[84:87]
	v_mfma_f32_16x16x32_bf16 v[80:83], v[162:165], v[204:207], v[80:83]
	v_mfma_f32_16x16x32_bf16 v[68:71], v[154:157], v[212:215], v[68:71]
	v_mfma_f32_16x16x32_bf16 v[64:67], v[162:165], v[212:215], v[64:67]
	s_setprio 0
	s_setprio 1
	v_mfma_f32_16x16x32_bf16 v[124:127], v[168:171], v[184:187], v[124:127]
	v_mfma_f32_16x16x32_bf16 v[120:123], v[176:179], v[184:187], v[120:123]
	v_mfma_f32_16x16x32_bf16 v[108:111], v[168:171], v[192:195], v[108:111]
	v_mfma_f32_16x16x32_bf16 v[104:107], v[176:179], v[192:195], v[104:107]
	v_mfma_f32_16x16x32_bf16 v[92:95], v[168:171], v[200:203], v[92:95]
	v_mfma_f32_16x16x32_bf16 v[88:91], v[176:179], v[200:203], v[88:91]
	v_mfma_f32_16x16x32_bf16 v[76:79], v[168:171], v[208:211], v[76:79]
	v_mfma_f32_16x16x32_bf16 v[72:75], v[176:179], v[208:211], v[72:75]
	v_mfma_f32_16x16x32_bf16 v[124:127], v[172:175], v[188:191], v[124:127]
	v_mfma_f32_16x16x32_bf16 v[120:123], v[180:183], v[188:191], v[120:123]
	v_mfma_f32_16x16x32_bf16 v[108:111], v[172:175], v[196:199], v[108:111]
	v_mfma_f32_16x16x32_bf16 v[104:107], v[180:183], v[196:199], v[104:107]
	v_mfma_f32_16x16x32_bf16 v[92:95], v[172:175], v[204:207], v[92:95]
	v_mfma_f32_16x16x32_bf16 v[88:91], v[180:183], v[204:207], v[88:91]
	v_mfma_f32_16x16x32_bf16 v[76:79], v[172:175], v[212:215], v[76:79]
	v_mfma_f32_16x16x32_bf16 v[72:75], v[180:183], v[212:215], v[72:75]
	s_setprio 0
	s_barrier
	s_add_i32 s4, s59, s47
	v_lshl_add_u64 v[216:217], v[216:217], 0, s[14:15]
	s_mov_b32 m0, s4
	ds_read_b128 v[184:187], v151 offset:49152
	ds_read_b128 v[188:191], v151 offset:50176
	ds_read_b128 v[192:195], v151 offset:51200
	ds_read_b128 v[196:199], v151 offset:52224
	ds_read_b128 v[200:203], v151 offset:53248
	ds_read_b128 v[204:207], v151 offset:54272
	ds_read_b128 v[208:211], v151 offset:55296
	ds_read_b128 v[212:215], v151 offset:56320
	global_load_lds_dwordx4 v[216:217], off
	s_add_i32 m0, s4, 0x2000
	s_add_u32 s4, s30, 0x80080
	v_lshl_add_u64 v[216:217], v[218:219], 0, s[14:15]
	s_addc_u32 s5, s31, 0
	s_add_i32 s30, s60, s47
	global_load_lds_dwordx4 v[216:217], off
	v_lshl_add_u64 v[216:217], s[4:5], 0, v[132:133]
	s_mov_b32 m0, s30
	s_nop 0
	global_load_lds_dwordx4 v[216:217], off
	v_lshl_add_u64 v[216:217], s[4:5], 0, v[128:129]
	s_add_i32 m0, s30, 0x2000
	s_nop 0
	global_load_lds_dwordx4 v[216:217], off
	v_lshl_add_u64 v[216:217], v[220:221], 0, s[14:15]
	s_mov_b32 m0, s39
	s_nop 0
	global_load_lds_dwordx4 v[216:217], off
	v_lshl_add_u64 v[216:217], v[222:223], 0, s[14:15]
	s_mov_b32 m0, s40
	s_nop 0
	global_load_lds_dwordx4 v[216:217], off
	s_waitcnt vmcnt(8)
	s_waitcnt lgkmcnt(0)
	s_barrier
; #define PG8_LDA(dst, b, h) do { _Pragma("unroll") for (int m = 0; m < 4; ++m) _Pragma("unroll") for (int k = 0; k < 2; ++k) dst[m][k] = *(const PG8_LAS bf16x8*)(lds + PG8_SA(b, h) + aoff + m * 2048 + k * 1024); } while (0)
; template <class Epi, class Sched, bool ALIGN_EPI = false, bool SP2 = false>
; __device__ __forceinline__ void gemm_phase(PG8_LAS unsigned char* lds, const Gemm g, const Sched& S, const Epi& E) {
;     ...
;             PG8_WAIT_V(8); PG8_WAIT_L(0); PG8_BAR; PG8_MMA(1, 0, At, B0); PG8_MMA(1, 1, At, B1); PG8_BAR; PG8_SCHED;
;             } else {
;             PG8_LDB(B0, 0, 0); PG8_SCHED; PG8_LDA(At, 0, 0); PG8_STAGE(PG8_SA(1, 1), a1 + hstepA, voffA);
;             PG8_WAIT_L(8); PG8_BAR; PG8_WAIT_L(0); PG8_MMA(0, 0, At, B0); PG8_BAR; PG8_SCHED;
;             PG8_LDB(B1, 0, 1); PG8_STAGE(PG8_SB(0, 0), b2, voffB);
;             PG8_BAR; PG8_WAIT_L(0); PG8_MMA(0, 1, At, B1); PG8_BAR;
;             PG8_LDA(At, 0, 1); PG8_STAGE(PG8_SA(0, 0), a2, voffA);
;             PG8_BAR; PG8_WAIT_L(0); PG8_MMA(1, 0, At, B0); PG8_BAR; PG8_SCHED;
;             PG8_STAGE(PG8_SB(0, 1), b2 + hstepB, voffB);
;             PG8_WAIT_V(6); PG8_BAR; PG8_MMA(1, 1, At, B1); PG8_BAR;
;             PG8_LDB(B0, 1, 0); PG8_SCHED; PG8_LDA(At, 1, 0); PG8_STAGE(PG8_SA(0, 1), a2 + hstepA, voffA);
;             PG8_WAIT_L(8); PG8_BAR; PG8_WAIT_L(0); PG8_MMA(0, 0, At, B0); PG8_BAR; PG8_SCHED;
;             PG8_LDB(B1, 1, 1); PG8_STAGE(PG8_SB(1, 0), b3, voffB);
;             PG8_BAR; PG8_WAIT_L(0); PG8_MMA(0, 1, At, B1); PG8_BAR;
;             PG8_LDA(At, 1, 1); PG8_STAGE(PG8_SA(1, 0), a3, voffA);
;             PG8_BAR; PG8_WAIT_L(0); PG8_MMA(1, 0, At, B0); PG8_BAR; PG8_SCHED;
;             PG8_STAGE(PG8_SB(1, 1), b3 + hstepB, voffB);
;             PG8_WAIT_V(6); PG8_BAR; PG8_MMA(1, 1, At, B1); PG8_BAR;
;             }
;         }
;         if constexpr (ALIGN_EPI) { if (wr == 0) PG8_BAR; }
;     __device__ __forceinline__ void operator()(const f32x4 (&acc)[2][2][4][2], const Unit& u, int wr, int wc, int fr, int fq) const {
;     ...
;             for (int m = 0; m < 4; ++m) { const int row = row0 + ai * HALF + m * 16; const float rs = row_rstd(ssq, row, fr, fq), rs2 = rs * rs, nrl = -1.4426950408889634f * rs;
;                 float o[8];
; #pragma unroll
;                 for (int n = 0; n < 2; ++n) { const f32x4 g = acc[ai][0][m][n], gu = g * acc[ai][1][m][n] * rs2;
	s_setprio 1
	s_waitcnt lgkmcnt(0)
	v_mfma_f32_16x16x32_bf16 v[52:55], v[144:147], v[184:187], v[52:55]
	v_mfma_f32_16x16x32_bf16 v[48:51], v[158:161], v[184:187], v[48:51]
	v_mfma_f32_16x16x32_bf16 v[36:39], v[144:147], v[192:195], v[36:39]
	v_mfma_f32_16x16x32_bf16 v[32:35], v[158:161], v[192:195], v[32:35]
	v_mfma_f32_16x16x32_bf16 v[20:23], v[144:147], v[200:203], v[20:23]
	v_mfma_f32_16x16x32_bf16 v[16:19], v[158:161], v[200:203], v[16:19]
	v_mfma_f32_16x16x32_bf16 v[8:11], v[144:147], v[208:211], v[8:11]
	v_mfma_f32_16x16x32_bf16 v[4:7], v[158:161], v[208:211], v[4:7]
	v_mfma_f32_16x16x32_bf16 v[52:55], v[154:157], v[188:191], v[52:55]
	v_mfma_f32_16x16x32_bf16 v[48:51], v[162:165], v[188:191], v[48:51]
	v_mfma_f32_16x16x32_bf16 v[36:39], v[154:157], v[196:199], v[36:39]
	v_mfma_f32_16x16x32_bf16 v[32:35], v[162:165], v[196:199], v[32:35]
	v_mfma_f32_16x16x32_bf16 v[20:23], v[154:157], v[204:207], v[20:23]
	v_mfma_f32_16x16x32_bf16 v[16:19], v[162:165], v[204:207], v[16:19]
	v_mfma_f32_16x16x32_bf16 v[8:11], v[154:157], v[212:215], v[8:11]
	v_mfma_f32_16x16x32_bf16 v[4:7], v[162:165], v[212:215], v[4:7]
	s_setprio 0
	s_setprio 1
	v_mfma_f32_16x16x32_bf16 v[60:63], v[168:171], v[184:187], v[60:63]
	v_mfma_f32_16x16x32_bf16 v[56:59], v[176:179], v[184:187], v[56:59]
	v_mfma_f32_16x16x32_bf16 v[44:47], v[168:171], v[192:195], v[44:47]
	v_mfma_f32_16x16x32_bf16 v[40:43], v[176:179], v[192:195], v[40:43]
	v_mfma_f32_16x16x32_bf16 v[28:31], v[168:171], v[200:203], v[28:31]
	v_mfma_f32_16x16x32_bf16 v[24:27], v[176:179], v[200:203], v[24:27]
	v_mfma_f32_16x16x32_bf16 v[12:15], v[168:171], v[208:211], v[12:15]
	v_mfma_f32_16x16x32_bf16 v[0:3], v[176:179], v[208:211], v[0:3]
	v_mfma_f32_16x16x32_bf16 v[60:63], v[172:175], v[188:191], v[60:63]
	v_mfma_f32_16x16x32_bf16 v[56:59], v[180:183], v[188:191], v[56:59]
	v_mfma_f32_16x16x32_bf16 v[44:47], v[172:175], v[196:199], v[44:47]
	v_mfma_f32_16x16x32_bf16 v[40:43], v[180:183], v[196:199], v[40:43]
	v_mfma_f32_16x16x32_bf16 v[28:31], v[172:175], v[204:207], v[28:31]
	v_mfma_f32_16x16x32_bf16 v[24:27], v[180:183], v[204:207], v[24:27]
	v_mfma_f32_16x16x32_bf16 v[12:15], v[172:175], v[212:215], v[12:15]
	v_mfma_f32_16x16x32_bf16 v[0:3], v[180:183], v[212:215], v[0:3]
	s_setprio 0
	s_barrier
	s_add_i32 s58, s58, 2
	s_add_u32 s28, s28, 0x100
	s_addc_u32 s29, s29, 0
	s_add_u32 s56, s56, 0x100
	s_addc_u32 s57, s57, 0
	s_cmp_gt_u32 s58, 29
	s_cbranch_scc0 .LBB0_1287
	s_and_b64 vcc, exec, s[48:49]
	s_cbranch_vccz .LBB0_1290
	s_barrier
.LBB0_1290:
	v_and_b32_e32 v153, 15, v167
	v_lshrrev_b32_e32 v154, 4, v167
	s_lshl_b32 s4, s26, 8
	s_add_i32 s4, s4, s78
	v_or_b32_e32 v155, s4, v153
	v_lshlrev_b32_e32 v156, 7, v155
	v_lshl_add_u32 v156, v154, 5, v156
	v_add_u32_e32 v157, 0x1000, v156
	v_add_u32_e32 v158, 0x4000, v156
	v_add_u32_e32 v159, 0x5000, v156
	global_load_dwordx4 v[168:171], v156, s[12:13]
	global_load_dwordx4 v[172:175], v156, s[12:13] offset:16
	global_load_dwordx4 v[176:179], v156, s[12:13] offset:2048
	global_load_dwordx4 v[180:183], v156, s[12:13] offset:2064
	global_load_dwordx4 v[184:187], v157, s[12:13]
	global_load_dwordx4 v[188:191], v157, s[12:13] offset:16
	global_load_dwordx4 v[192:195], v157, s[12:13] offset:2048
	global_load_dwordx4 v[196:199], v157, s[12:13] offset:2064
	global_load_dwordx4 v[200:203], v158, s[12:13]
	global_load_dwordx4 v[204:207], v158, s[12:13] offset:16
	global_load_dwordx4 v[208:211], v158, s[12:13] offset:2048
	global_load_dwordx4 v[212:215], v158, s[12:13] offset:2064
	global_load_dwordx4 v[216:219], v159, s[12:13]
	global_load_dwordx4 v[220:223], v159, s[12:13] offset:16
	global_load_dwordx4 v[224:227], v159, s[12:13] offset:2048
	global_load_dwordx4 v[228:231], v159, s[12:13] offset:2064
	v_xor_b32_e32 v160, 16, v167
	v_xor_b32_e32 v161, 32, v167
	v_lshlrev_b32_e32 v160, 2, v160
	v_lshlrev_b32_e32 v161, 2, v161
	s_lshl_b32 s4, s53, 7
	s_or_b32 s4, s4, s82
	v_lshl_add_u32 v162, v154, 3, s4
	v_lshlrev_b32_e32 v162, 1, v162
	v_mul_u32_u24_e32 v163, 0x2c00, v155
	v_add_u32_e32 v162, v162, v163
	v_mul_f32_e32 v124, v116, v124
	v_mul_f32_e32 v125, v117, v125
	v_mul_f32_e32 v126, v118, v126
	v_mul_f32_e32 v127, v119, v127
	v_mul_f32_e32 v120, v112, v120
	v_mul_f32_e32 v121, v113, v121
	v_mul_f32_e32 v122, v114, v122
	v_mul_f32_e32 v123, v115, v123
	v_mul_f32_e32 v108, v100, v108
	v_mul_f32_e32 v109, v101, v109
	v_mul_f32_e32 v110, v102, v110
	v_mul_f32_e32 v111, v103, v111
	v_mul_f32_e32 v104, v96, v104
	v_mul_f32_e32 v105, v97, v105
	v_mul_f32_e32 v106, v98, v106
	v_mul_f32_e32 v107, v99, v107
	v_mul_f32_e32 v92, v84, v92
	v_mul_f32_e32 v93, v85, v93
	v_mul_f32_e32 v94, v86, v94
	v_mul_f32_e32 v95, v87, v95
	v_mul_f32_e32 v88, v80, v88
	v_mul_f32_e32 v89, v81, v89
	v_mul_f32_e32 v90, v82, v90
	v_mul_f32_e32 v91, v83, v91
	v_mul_f32_e32 v76, v68, v76
	v_mul_f32_e32 v77, v69, v77
	v_mul_f32_e32 v78, v70, v78
	v_mul_f32_e32 v79, v71, v79
	v_mul_f32_e32 v72, v64, v72
	v_mul_f32_e32 v73, v65, v73
	v_mul_f32_e32 v74, v66, v74
	v_mul_f32_e32 v75, v67, v75
	v_mul_f32_e32 v60, v52, v60
	v_mul_f32_e32 v61, v53, v61
	v_mul_f32_e32 v62, v54, v62
	v_mul_f32_e32 v63, v55, v63
	v_mul_f32_e32 v56, v48, v56
	v_mul_f32_e32 v57, v49, v57
	v_mul_f32_e32 v58, v50, v58
	v_mul_f32_e32 v59, v51, v59
	v_mul_f32_e32 v44, v36, v44
	v_mul_f32_e32 v45, v37, v45
	v_mul_f32_e32 v46, v38, v46
	v_mul_f32_e32 v47, v39, v47
	v_mul_f32_e32 v40, v32, v40
	v_mul_f32_e32 v41, v33, v41
	v_mul_f32_e32 v42, v34, v42
	v_mul_f32_e32 v43, v35, v43
	v_mul_f32_e32 v28, v20, v28
	v_mul_f32_e32 v29, v21, v29
	v_mul_f32_e32 v30, v22, v30
	v_mul_f32_e32 v31, v23, v31
	v_mul_f32_e32 v24, v16, v24
	v_mul_f32_e32 v25, v17, v25
	v_mul_f32_e32 v26, v18, v26
	v_mul_f32_e32 v27, v19, v27
	v_mul_f32_e32 v12, v8, v12
	v_mul_f32_e32 v13, v9, v13
	v_mul_f32_e32 v14, v10, v14
	v_mul_f32_e32 v15, v11, v15
	v_mul_f32_e32 v0, v4, v0
	v_mul_f32_e32 v1, v5, v1
	v_mul_f32_e32 v2, v6, v2
	v_mul_f32_e32 v3, v7, v3
	s_waitcnt vmcnt(0)
; __device__ __forceinline__ unsigned cvt_pk_bf16(float lo, float hi) { unsigned r; asm volatile("v_cvt_pk_bf16_f32 %0, %1, %2" : "=v"(r) : "v"(lo), "v"(hi)); return r; }
; __device__ __forceinline__ float shx(float v, int mask, int lane) { return __int_as_float(__builtin_amdgcn_ds_bpermute((lane ^ mask) << 2, __float_as_int(v))); }
; __device__ __forceinline__ float row_rstd(const float* ssqp, int row, int fr, int fq) {
;     const f32x4 p0 = *(const f32x4*)(ssqp + (size_t)row * 32 + fq * 8), p1 = *(const f32x4*)(ssqp + (size_t)row * 32 + fq * 8 + 4);
;     float t = ((p0[0] + p0[1]) + (p0[2] + p0[3])) + ((p1[0] + p1[1]) + (p1[2] + p1[3])); const int ln = fr + 16 * fq;
;     t += shx(t, 16, ln); t += shx(t, 32, ln);
;     return rsqrtf(t * (1.0f / 2048.0f) + RMS_EPS);
;     __device__ __forceinline__ void operator()(const f32x4 (&acc)[2][2][4][2], const Unit& u, int wr, int wc, int fr, int fq) const {
;     ...
;             for (int m = 0; m < 4; ++m) { const int row = row0 + ai * HALF + m * 16; const float rs = row_rstd(ssq, row, fr, fq), rs2 = rs * rs, nrl = -1.4426950408889634f * rs;
;                 float o[8];
; #pragma unroll
;                 for (int n = 0; n < 2; ++n) { const f32x4 g = acc[ai][0][m][n], gu = g * acc[ai][1][m][n] * rs2;
; #pragma unroll
;                     for (int j = 0; j < 4; ++j) o[4 * n + j] = gu[j] * __builtin_amdgcn_rcpf(1.0f + __builtin_amdgcn_exp2f(g[j] * nrl)); }
;                 u32x4 w; w.x = cvt_pk_bf16(o[0], o[1]); w.y = cvt_pk_bf16(o[2], o[3]); w.z = cvt_pk_bf16(o[4], o[5]); w.w = cvt_pk_bf16(o[6], o[7]);
;                 *(u32x4*)(ACT + (size_t)row * 5632 + ch0) = w;
	v_add_f32_e32 v168, v168, v169
	v_add_f32_e32 v176, v176, v177
	v_add_f32_e32 v184, v184, v185
	v_add_f32_e32 v192, v192, v193
	v_add_f32_e32 v200, v200, v201
	v_add_f32_e32 v208, v208, v209
	v_add_f32_e32 v216, v216, v217
	v_add_f32_e32 v224, v224, v225
	v_add_f32_e32 v170, v170, v171
	v_add_f32_e32 v178, v178, v179
	v_add_f32_e32 v186, v186, v187
	v_add_f32_e32 v194, v194, v195
	v_add_f32_e32 v202, v202, v203
	v_add_f32_e32 v210, v210, v211
	v_add_f32_e32 v218, v218, v219
	v_add_f32_e32 v226, v226, v227
	v_add_f32_e32 v172, v172, v173
	v_add_f32_e32 v180, v180, v181
	v_add_f32_e32 v188, v188, v189
	v_add_f32_e32 v196, v196, v197
	v_add_f32_e32 v204, v204, v205
	v_add_f32_e32 v212, v212, v213
	v_add_f32_e32 v220, v220, v221
	v_add_f32_e32 v228, v228, v229
	v_add_f32_e32 v174, v174, v175
	v_add_f32_e32 v182, v182, v183
	v_add_f32_e32 v190, v190, v191
	v_add_f32_e32 v198, v198, v199
	v_add_f32_e32 v206, v206, v207
	v_add_f32_e32 v214, v214, v215
	v_add_f32_e32 v222, v222, v223
	v_add_f32_e32 v230, v230, v231
	v_add_f32_e32 v168, v168, v170
	v_add_f32_e32 v176, v176, v178
	v_add_f32_e32 v184, v184, v186
	v_add_f32_e32 v192, v192, v194
	v_add_f32_e32 v200, v200, v202
	v_add_f32_e32 v208, v208, v210
	v_add_f32_e32 v216, v216, v218
	v_add_f32_e32 v224, v224, v226
	v_add_f32_e32 v172, v172, v174
	v_add_f32_e32 v180, v180, v182
	v_add_f32_e32 v188, v188, v190
	v_add_f32_e32 v196, v196, v198
	v_add_f32_e32 v204, v204, v206
	v_add_f32_e32 v212, v212, v214
	v_add_f32_e32 v220, v220, v222
	v_add_f32_e32 v228, v228, v230
	v_add_f32_e32 v168, v168, v172
	v_add_f32_e32 v176, v176, v180
	v_add_f32_e32 v184, v184, v188
	v_add_f32_e32 v192, v192, v196
	v_add_f32_e32 v200, v200, v204
	v_add_f32_e32 v208, v208, v212
	v_add_f32_e32 v216, v216, v220
	v_add_f32_e32 v224, v224, v228
	ds_bpermute_b32 v240, v160, v168
	ds_bpermute_b32 v241, v160, v176
	ds_bpermute_b32 v242, v160, v184
	ds_bpermute_b32 v243, v160, v192
	ds_bpermute_b32 v244, v160, v200
	ds_bpermute_b32 v245, v160, v208
	ds_bpermute_b32 v246, v160, v216
	ds_bpermute_b32 v247, v160, v224
	s_waitcnt lgkmcnt(0)
	v_add_f32_e32 v168, v168, v240
	v_add_f32_e32 v176, v176, v241
	v_add_f32_e32 v184, v184, v242
	v_add_f32_e32 v192, v192, v243
	v_add_f32_e32 v200, v200, v244
	v_add_f32_e32 v208, v208, v245
	v_add_f32_e32 v216, v216, v246
	v_add_f32_e32 v224, v224, v247
	ds_bpermute_b32 v240, v161, v168
	ds_bpermute_b32 v241, v161, v176
	ds_bpermute_b32 v242, v161, v184
	ds_bpermute_b32 v243, v161, v192
	ds_bpermute_b32 v244, v161, v200
	ds_bpermute_b32 v245, v161, v208
	ds_bpermute_b32 v246, v161, v216
	ds_bpermute_b32 v247, v161, v224
	s_waitcnt lgkmcnt(0)
	v_add_f32_e32 v168, v168, v240
	v_add_f32_e32 v176, v176, v241
	v_add_f32_e32 v184, v184, v242
	v_add_f32_e32 v192, v192, v243
	v_add_f32_e32 v200, v200, v244
	v_add_f32_e32 v208, v208, v245
	v_add_f32_e32 v216, v216, v246
	v_add_f32_e32 v224, v224, v247
	v_fmamk_f32 v168, v168, 0x3a000000, v152
	v_fmamk_f32 v176, v176, 0x3a000000, v152
	v_fmamk_f32 v184, v184, 0x3a000000, v152
	v_fmamk_f32 v192, v192, 0x3a000000, v152
	v_fmamk_f32 v200, v200, 0x3a000000, v152
	v_fmamk_f32 v208, v208, 0x3a000000, v152
	v_fmamk_f32 v216, v216, 0x3a000000, v152
	v_fmamk_f32 v224, v224, 0x3a000000, v152
	v_rsq_f32_e32 v232, v168
	v_rsq_f32_e32 v233, v176
	v_rsq_f32_e32 v234, v184
	v_rsq_f32_e32 v235, v192
	v_rsq_f32_e32 v236, v200
	v_rsq_f32_e32 v237, v208
	v_rsq_f32_e32 v238, v216
	v_rsq_f32_e32 v239, v224
	v_mul_f32_e32 v169, 0xbfb8aa3b, v232
	v_mul_f32_e32 v177, 0xbfb8aa3b, v233
	v_mul_f32_e32 v185, 0xbfb8aa3b, v234
	v_mul_f32_e32 v193, 0xbfb8aa3b, v235
	v_mul_f32_e32 v201, 0xbfb8aa3b, v236
	v_mul_f32_e32 v209, 0xbfb8aa3b, v237
	v_mul_f32_e32 v217, 0xbfb8aa3b, v238
	v_mul_f32_e32 v225, 0xbfb8aa3b, v239
	v_mul_f32_e32 v170, v232, v232
	v_mul_f32_e32 v178, v233, v233
	v_mul_f32_e32 v186, v234, v234
	v_mul_f32_e32 v194, v235, v235
	v_mul_f32_e32 v202, v236, v236
	v_mul_f32_e32 v210, v237, v237
	v_mul_f32_e32 v218, v238, v238
	v_mul_f32_e32 v226, v239, v239
	v_mov_b32_e32 v171, v162
	v_mul_f32_e32 v116, v116, v169
	v_mul_f32_e32 v117, v117, v169
	v_mul_f32_e32 v118, v118, v169
	v_mul_f32_e32 v119, v119, v169
	v_mul_f32_e32 v112, v112, v169
	v_mul_f32_e32 v113, v113, v169
	v_mul_f32_e32 v114, v114, v169
	v_mul_f32_e32 v115, v115, v169
	v_exp_f32_e32 v116, v116
	v_exp_f32_e32 v117, v117
	v_exp_f32_e32 v118, v118
	v_exp_f32_e32 v119, v119
	v_exp_f32_e32 v112, v112
	v_exp_f32_e32 v113, v113
	v_exp_f32_e32 v114, v114
	v_exp_f32_e32 v115, v115
	v_add_f32_e32 v116, 1.0, v116
	v_add_f32_e32 v117, 1.0, v117
	v_add_f32_e32 v118, 1.0, v118
	v_add_f32_e32 v119, 1.0, v119
	v_add_f32_e32 v112, 1.0, v112
	v_add_f32_e32 v113, 1.0, v113
	v_add_f32_e32 v114, 1.0, v114
	v_add_f32_e32 v115, 1.0, v115
	v_rcp_f32_e32 v116, v116
	v_rcp_f32_e32 v117, v117
	v_rcp_f32_e32 v118, v118
	v_rcp_f32_e32 v119, v119
	v_rcp_f32_e32 v112, v112
	v_rcp_f32_e32 v113, v113
	v_rcp_f32_e32 v114, v114
	v_rcp_f32_e32 v115, v115
	v_mul_f32_e32 v124, v124, v170
	v_mul_f32_e32 v125, v125, v170
	v_mul_f32_e32 v126, v126, v170
	v_mul_f32_e32 v127, v127, v170
	v_mul_f32_e32 v120, v120, v170
	v_mul_f32_e32 v121, v121, v170
	v_mul_f32_e32 v122, v122, v170
	v_mul_f32_e32 v123, v123, v170
	v_mul_f32_e32 v124, v124, v116
	v_mul_f32_e32 v125, v125, v117
	v_mul_f32_e32 v126, v126, v118
	v_mul_f32_e32 v127, v127, v119
	v_mul_f32_e32 v120, v120, v112
	v_mul_f32_e32 v121, v121, v113
	v_mul_f32_e32 v122, v122, v114
	v_mul_f32_e32 v123, v123, v115
	v_cvt_pk_bf16_f32 v116, v124, v125
	v_cvt_pk_bf16_f32 v117, v126, v127
	v_cvt_pk_bf16_f32 v118, v120, v121
	v_cvt_pk_bf16_f32 v119, v122, v123
	global_store_dwordx4 v171, v[116:119], s[10:11]
; __device__ __forceinline__ unsigned cvt_pk_bf16(float lo, float hi) { unsigned r; asm volatile("v_cvt_pk_bf16_f32 %0, %1, %2" : "=v"(r) : "v"(lo), "v"(hi)); return r; }
;     __device__ __forceinline__ void operator()(const f32x4 (&acc)[2][2][4][2], const Unit& u, int wr, int wc, int fr, int fq) const {
;     ...
;             for (int m = 0; m < 4; ++m) { const int row = row0 + ai * HALF + m * 16; const float rs = row_rstd(ssq, row, fr, fq), rs2 = rs * rs, nrl = -1.4426950408889634f * rs;
;                 float o[8];
; #pragma unroll
;                 for (int n = 0; n < 2; ++n) { const f32x4 g = acc[ai][0][m][n], gu = g * acc[ai][1][m][n] * rs2;
; #pragma unroll
;                     for (int j = 0; j < 4; ++j) o[4 * n + j] = gu[j] * __builtin_amdgcn_rcpf(1.0f + __builtin_amdgcn_exp2f(g[j] * nrl)); }
;                 u32x4 w; w.x = cvt_pk_bf16(o[0], o[1]); w.y = cvt_pk_bf16(o[2], o[3]); w.z = cvt_pk_bf16(o[4], o[5]); w.w = cvt_pk_bf16(o[6], o[7]);
;                 *(u32x4*)(ACT + (size_t)row * 5632 + ch0) = w;
	v_add_u32_e32 v179, 0x2c000, v162
	v_mul_f32_e32 v100, v100, v177
	v_mul_f32_e32 v101, v101, v177
	v_mul_f32_e32 v102, v102, v177
	v_mul_f32_e32 v103, v103, v177
	v_mul_f32_e32 v96, v96, v177
	v_mul_f32_e32 v97, v97, v177
	v_mul_f32_e32 v98, v98, v177
	v_mul_f32_e32 v99, v99, v177
	v_exp_f32_e32 v100, v100
	v_exp_f32_e32 v101, v101
	v_exp_f32_e32 v102, v102
	v_exp_f32_e32 v103, v103
	v_exp_f32_e32 v96, v96
	v_exp_f32_e32 v97, v97
	v_exp_f32_e32 v98, v98
	v_exp_f32_e32 v99, v99
	v_add_f32_e32 v100, 1.0, v100
	v_add_f32_e32 v101, 1.0, v101
	v_add_f32_e32 v102, 1.0, v102
	v_add_f32_e32 v103, 1.0, v103
	v_add_f32_e32 v96, 1.0, v96
	v_add_f32_e32 v97, 1.0, v97
	v_add_f32_e32 v98, 1.0, v98
	v_add_f32_e32 v99, 1.0, v99
	v_rcp_f32_e32 v100, v100
	v_rcp_f32_e32 v101, v101
	v_rcp_f32_e32 v102, v102
	v_rcp_f32_e32 v103, v103
	v_rcp_f32_e32 v96, v96
	v_rcp_f32_e32 v97, v97
	v_rcp_f32_e32 v98, v98
	v_rcp_f32_e32 v99, v99
	v_mul_f32_e32 v108, v108, v178
	v_mul_f32_e32 v109, v109, v178
	v_mul_f32_e32 v110, v110, v178
	v_mul_f32_e32 v111, v111, v178
	v_mul_f32_e32 v104, v104, v178
	v_mul_f32_e32 v105, v105, v178
	v_mul_f32_e32 v106, v106, v178
	v_mul_f32_e32 v107, v107, v178
	v_mul_f32_e32 v108, v108, v100
	v_mul_f32_e32 v109, v109, v101
	v_mul_f32_e32 v110, v110, v102
	v_mul_f32_e32 v111, v111, v103
	v_mul_f32_e32 v104, v104, v96
	v_mul_f32_e32 v105, v105, v97
	v_mul_f32_e32 v106, v106, v98
	v_mul_f32_e32 v107, v107, v99
	v_cvt_pk_bf16_f32 v100, v108, v109
	v_cvt_pk_bf16_f32 v101, v110, v111
	v_cvt_pk_bf16_f32 v102, v104, v105
	v_cvt_pk_bf16_f32 v103, v106, v107
	global_store_dwordx4 v179, v[100:103], s[10:11]
	v_add_u32_e32 v187, 0x58000, v162
	v_mul_f32_e32 v84, v84, v185
	v_mul_f32_e32 v85, v85, v185
	v_mul_f32_e32 v86, v86, v185
	v_mul_f32_e32 v87, v87, v185
	v_mul_f32_e32 v80, v80, v185
	v_mul_f32_e32 v81, v81, v185
	v_mul_f32_e32 v82, v82, v185
	v_mul_f32_e32 v83, v83, v185
	v_exp_f32_e32 v84, v84
	v_exp_f32_e32 v85, v85
	v_exp_f32_e32 v86, v86
	v_exp_f32_e32 v87, v87
	v_exp_f32_e32 v80, v80
	v_exp_f32_e32 v81, v81
	v_exp_f32_e32 v82, v82
	v_exp_f32_e32 v83, v83
	v_add_f32_e32 v84, 1.0, v84
	v_add_f32_e32 v85, 1.0, v85
	v_add_f32_e32 v86, 1.0, v86
	v_add_f32_e32 v87, 1.0, v87
	v_add_f32_e32 v80, 1.0, v80
	v_add_f32_e32 v81, 1.0, v81
	v_add_f32_e32 v82, 1.0, v82
	v_add_f32_e32 v83, 1.0, v83
	v_rcp_f32_e32 v84, v84
	v_rcp_f32_e32 v85, v85
	v_rcp_f32_e32 v86, v86
	v_rcp_f32_e32 v87, v87
	v_rcp_f32_e32 v80, v80
	v_rcp_f32_e32 v81, v81
	v_rcp_f32_e32 v82, v82
	v_rcp_f32_e32 v83, v83
	v_mul_f32_e32 v92, v92, v186
	v_mul_f32_e32 v93, v93, v186
	v_mul_f32_e32 v94, v94, v186
	v_mul_f32_e32 v95, v95, v186
	v_mul_f32_e32 v88, v88, v186
	v_mul_f32_e32 v89, v89, v186
	v_mul_f32_e32 v90, v90, v186
	v_mul_f32_e32 v91, v91, v186
	v_mul_f32_e32 v92, v92, v84
	v_mul_f32_e32 v93, v93, v85
	v_mul_f32_e32 v94, v94, v86
	v_mul_f32_e32 v95, v95, v87
	v_mul_f32_e32 v88, v88, v80
	v_mul_f32_e32 v89, v89, v81
	v_mul_f32_e32 v90, v90, v82
	v_mul_f32_e32 v91, v91, v83
	v_cvt_pk_bf16_f32 v84, v92, v93
	v_cvt_pk_bf16_f32 v85, v94, v95
	v_cvt_pk_bf16_f32 v86, v88, v89
	v_cvt_pk_bf16_f32 v87, v90, v91
	global_store_dwordx4 v187, v[84:87], s[10:11]
	v_add_u32_e32 v195, 0x84000, v162
	v_mul_f32_e32 v68, v68, v193
	v_mul_f32_e32 v69, v69, v193
	v_mul_f32_e32 v70, v70, v193
	v_mul_f32_e32 v71, v71, v193
	v_mul_f32_e32 v64, v64, v193
	v_mul_f32_e32 v65, v65, v193
	v_mul_f32_e32 v66, v66, v193
	v_mul_f32_e32 v67, v67, v193
	v_exp_f32_e32 v68, v68
	v_exp_f32_e32 v69, v69
	v_exp_f32_e32 v70, v70
	v_exp_f32_e32 v71, v71
	v_exp_f32_e32 v64, v64
	v_exp_f32_e32 v65, v65
	v_exp_f32_e32 v66, v66
	v_exp_f32_e32 v67, v67
	v_add_f32_e32 v68, 1.0, v68
	v_add_f32_e32 v69, 1.0, v69
	v_add_f32_e32 v70, 1.0, v70
	v_add_f32_e32 v71, 1.0, v71
	v_add_f32_e32 v64, 1.0, v64
	v_add_f32_e32 v65, 1.0, v65
	v_add_f32_e32 v66, 1.0, v66
	v_add_f32_e32 v67, 1.0, v67
	v_rcp_f32_e32 v68, v68
	v_rcp_f32_e32 v69, v69
	v_rcp_f32_e32 v70, v70
	v_rcp_f32_e32 v71, v71
	v_rcp_f32_e32 v64, v64
	v_rcp_f32_e32 v65, v65
	v_rcp_f32_e32 v66, v66
	v_rcp_f32_e32 v67, v67
	v_mul_f32_e32 v76, v76, v194
	v_mul_f32_e32 v77, v77, v194
	v_mul_f32_e32 v78, v78, v194
	v_mul_f32_e32 v79, v79, v194
	v_mul_f32_e32 v72, v72, v194
	v_mul_f32_e32 v73, v73, v194
	v_mul_f32_e32 v74, v74, v194
	v_mul_f32_e32 v75, v75, v194
	v_mul_f32_e32 v76, v76, v68
	v_mul_f32_e32 v77, v77, v69
	v_mul_f32_e32 v78, v78, v70
	v_mul_f32_e32 v79, v79, v71
	v_mul_f32_e32 v72, v72, v64
	v_mul_f32_e32 v73, v73, v65
	v_mul_f32_e32 v74, v74, v66
	v_mul_f32_e32 v75, v75, v67
	v_cvt_pk_bf16_f32 v68, v76, v77
	v_cvt_pk_bf16_f32 v69, v78, v79
	v_cvt_pk_bf16_f32 v70, v72, v73
	v_cvt_pk_bf16_f32 v71, v74, v75
	global_store_dwordx4 v195, v[68:71], s[10:11]
	v_add_u32_e32 v203, 0x160000, v162
	v_mul_f32_e32 v52, v52, v201
	v_mul_f32_e32 v53, v53, v201
	v_mul_f32_e32 v54, v54, v201
	v_mul_f32_e32 v55, v55, v201
	v_mul_f32_e32 v48, v48, v201
	v_mul_f32_e32 v49, v49, v201
	v_mul_f32_e32 v50, v50, v201
	v_mul_f32_e32 v51, v51, v201
	v_exp_f32_e32 v52, v52
	v_exp_f32_e32 v53, v53
	v_exp_f32_e32 v54, v54
	v_exp_f32_e32 v55, v55
	v_exp_f32_e32 v48, v48
	v_exp_f32_e32 v49, v49
	v_exp_f32_e32 v50, v50
	v_exp_f32_e32 v51, v51
	v_add_f32_e32 v52, 1.0, v52
	v_add_f32_e32 v53, 1.0, v53
	v_add_f32_e32 v54, 1.0, v54
	v_add_f32_e32 v55, 1.0, v55
	v_add_f32_e32 v48, 1.0, v48
	v_add_f32_e32 v49, 1.0, v49
	v_add_f32_e32 v50, 1.0, v50
	v_add_f32_e32 v51, 1.0, v51
	v_rcp_f32_e32 v52, v52
	v_rcp_f32_e32 v53, v53
	v_rcp_f32_e32 v54, v54
; __device__ __forceinline__ unsigned cvt_pk_bf16(float lo, float hi) { unsigned r; asm volatile("v_cvt_pk_bf16_f32 %0, %1, %2" : "=v"(r) : "v"(lo), "v"(hi)); return r; }
; #define PG8_BAR __builtin_amdgcn_s_barrier()
; template <class Epi, class Sched, bool ALIGN_EPI = false, bool SP2 = false>
; __device__ __forceinline__ void gemm_phase(PG8_LAS unsigned char* lds, const Gemm g, const Sched& S, const Epi& E) {
;     ...
;         if (!has_next) break;
; #pragma unroll
;         for (int a = 0; a < 2; ++a)
; #pragma unroll
;             for (int b = 0; b < 2; ++b)
; #pragma unroll
;                 for (int m = 0; m < 4; ++m)
; #pragma unroll
;                     for (int n = 0; n < 2; ++n) acc[a][b][m][n] = (f32x4){0.f, 0.f, 0.f, 0.f};
;         cur = nxt; cA = nA; cB = nB; ++ui;
;         if constexpr (ALIGN_EPI) { if (wr == 1) PG8_BAR; }
;     __device__ __forceinline__ void operator()(const f32x4 (&acc)[2][2][4][2], const Unit& u, int wr, int wc, int fr, int fq) const {
;     ...
;             for (int m = 0; m < 4; ++m) { const int row = row0 + ai * HALF + m * 16; const float rs = row_rstd(ssq, row, fr, fq), rs2 = rs * rs, nrl = -1.4426950408889634f * rs;
;                 float o[8];
; #pragma unroll
;                 for (int n = 0; n < 2; ++n) { const f32x4 g = acc[ai][0][m][n], gu = g * acc[ai][1][m][n] * rs2;
; #pragma unroll
;                     for (int j = 0; j < 4; ++j) o[4 * n + j] = gu[j] * __builtin_amdgcn_rcpf(1.0f + __builtin_amdgcn_exp2f(g[j] * nrl)); }
;                 u32x4 w; w.x = cvt_pk_bf16(o[0], o[1]); w.y = cvt_pk_bf16(o[2], o[3]); w.z = cvt_pk_bf16(o[4], o[5]); w.w = cvt_pk_bf16(o[6], o[7]);
;                 *(u32x4*)(ACT + (size_t)row * 5632 + ch0) = w;
	v_rcp_f32_e32 v55, v55
	v_rcp_f32_e32 v48, v48
	v_rcp_f32_e32 v49, v49
	v_rcp_f32_e32 v50, v50
	v_rcp_f32_e32 v51, v51
	v_mul_f32_e32 v60, v60, v202
	v_mul_f32_e32 v61, v61, v202
	v_mul_f32_e32 v62, v62, v202
	v_mul_f32_e32 v63, v63, v202
	v_mul_f32_e32 v56, v56, v202
	v_mul_f32_e32 v57, v57, v202
	v_mul_f32_e32 v58, v58, v202
	v_mul_f32_e32 v59, v59, v202
	v_mul_f32_e32 v60, v60, v52
	v_mul_f32_e32 v61, v61, v53
	v_mul_f32_e32 v62, v62, v54
	v_mul_f32_e32 v63, v63, v55
	v_mul_f32_e32 v56, v56, v48
	v_mul_f32_e32 v57, v57, v49
	v_mul_f32_e32 v58, v58, v50
	v_mul_f32_e32 v59, v59, v51
	v_cvt_pk_bf16_f32 v52, v60, v61
	v_cvt_pk_bf16_f32 v53, v62, v63
	v_cvt_pk_bf16_f32 v54, v56, v57
	v_cvt_pk_bf16_f32 v55, v58, v59
	global_store_dwordx4 v203, v[52:55], s[10:11]
	v_add_u32_e32 v211, 0x18c000, v162
	v_mul_f32_e32 v36, v36, v209
	v_mul_f32_e32 v37, v37, v209
	v_mul_f32_e32 v38, v38, v209
	v_mul_f32_e32 v39, v39, v209
	v_mul_f32_e32 v32, v32, v209
	v_mul_f32_e32 v33, v33, v209
	v_mul_f32_e32 v34, v34, v209
	v_mul_f32_e32 v35, v35, v209
	v_exp_f32_e32 v36, v36
	v_exp_f32_e32 v37, v37
	v_exp_f32_e32 v38, v38
	v_exp_f32_e32 v39, v39
	v_exp_f32_e32 v32, v32
	v_exp_f32_e32 v33, v33
	v_exp_f32_e32 v34, v34
	v_exp_f32_e32 v35, v35
	v_add_f32_e32 v36, 1.0, v36
	v_add_f32_e32 v37, 1.0, v37
	v_add_f32_e32 v38, 1.0, v38
	v_add_f32_e32 v39, 1.0, v39
	v_add_f32_e32 v32, 1.0, v32
	v_add_f32_e32 v33, 1.0, v33
	v_add_f32_e32 v34, 1.0, v34
	v_add_f32_e32 v35, 1.0, v35
	v_rcp_f32_e32 v36, v36
	v_rcp_f32_e32 v37, v37
	v_rcp_f32_e32 v38, v38
	v_rcp_f32_e32 v39, v39
	v_rcp_f32_e32 v32, v32
	v_rcp_f32_e32 v33, v33
	v_rcp_f32_e32 v34, v34
	v_rcp_f32_e32 v35, v35
	v_mul_f32_e32 v44, v44, v210
	v_mul_f32_e32 v45, v45, v210
	v_mul_f32_e32 v46, v46, v210
	v_mul_f32_e32 v47, v47, v210
	v_mul_f32_e32 v40, v40, v210
	v_mul_f32_e32 v41, v41, v210
	v_mul_f32_e32 v42, v42, v210
	v_mul_f32_e32 v43, v43, v210
	v_mul_f32_e32 v44, v44, v36
	v_mul_f32_e32 v45, v45, v37
	v_mul_f32_e32 v46, v46, v38
	v_mul_f32_e32 v47, v47, v39
	v_mul_f32_e32 v40, v40, v32
	v_mul_f32_e32 v41, v41, v33
	v_mul_f32_e32 v42, v42, v34
	v_mul_f32_e32 v43, v43, v35
	v_cvt_pk_bf16_f32 v36, v44, v45
	v_cvt_pk_bf16_f32 v37, v46, v47
	v_cvt_pk_bf16_f32 v38, v40, v41
	v_cvt_pk_bf16_f32 v39, v42, v43
	global_store_dwordx4 v211, v[36:39], s[10:11]
	v_add_u32_e32 v219, 0x1b8000, v162
	v_mul_f32_e32 v20, v20, v217
	v_mul_f32_e32 v21, v21, v217
	v_mul_f32_e32 v22, v22, v217
	v_mul_f32_e32 v23, v23, v217
	v_mul_f32_e32 v16, v16, v217
	v_mul_f32_e32 v17, v17, v217
	v_mul_f32_e32 v18, v18, v217
	v_mul_f32_e32 v19, v19, v217
	v_exp_f32_e32 v20, v20
	v_exp_f32_e32 v21, v21
	v_exp_f32_e32 v22, v22
	v_exp_f32_e32 v23, v23
	v_exp_f32_e32 v16, v16
	v_exp_f32_e32 v17, v17
	v_exp_f32_e32 v18, v18
	v_exp_f32_e32 v19, v19
	v_add_f32_e32 v20, 1.0, v20
	v_add_f32_e32 v21, 1.0, v21
	v_add_f32_e32 v22, 1.0, v22
	v_add_f32_e32 v23, 1.0, v23
	v_add_f32_e32 v16, 1.0, v16
	v_add_f32_e32 v17, 1.0, v17
	v_add_f32_e32 v18, 1.0, v18
	v_add_f32_e32 v19, 1.0, v19
	v_rcp_f32_e32 v20, v20
	v_rcp_f32_e32 v21, v21
	v_rcp_f32_e32 v22, v22
	v_rcp_f32_e32 v23, v23
	v_rcp_f32_e32 v16, v16
	v_rcp_f32_e32 v17, v17
	v_rcp_f32_e32 v18, v18
	v_rcp_f32_e32 v19, v19
	v_mul_f32_e32 v28, v28, v218
	v_mul_f32_e32 v29, v29, v218
	v_mul_f32_e32 v30, v30, v218
	v_mul_f32_e32 v31, v31, v218
	v_mul_f32_e32 v24, v24, v218
	v_mul_f32_e32 v25, v25, v218
	v_mul_f32_e32 v26, v26, v218
	v_mul_f32_e32 v27, v27, v218
	v_mul_f32_e32 v28, v28, v20
	v_mul_f32_e32 v29, v29, v21
	v_mul_f32_e32 v30, v30, v22
	v_mul_f32_e32 v31, v31, v23
	v_mul_f32_e32 v24, v24, v16
	v_mul_f32_e32 v25, v25, v17
	v_mul_f32_e32 v26, v26, v18
	v_mul_f32_e32 v27, v27, v19
	v_cvt_pk_bf16_f32 v20, v28, v29
	v_cvt_pk_bf16_f32 v21, v30, v31
	v_cvt_pk_bf16_f32 v22, v24, v25
	v_cvt_pk_bf16_f32 v23, v26, v27
	global_store_dwordx4 v219, v[20:23], s[10:11]
	v_add_u32_e32 v227, 0x1e4000, v162
	v_mul_f32_e32 v8, v8, v225
	v_mul_f32_e32 v9, v9, v225
	v_mul_f32_e32 v10, v10, v225
	v_mul_f32_e32 v11, v11, v225
	v_mul_f32_e32 v4, v4, v225
	v_mul_f32_e32 v5, v5, v225
	v_mul_f32_e32 v6, v6, v225
	v_mul_f32_e32 v7, v7, v225
	v_exp_f32_e32 v8, v8
	v_exp_f32_e32 v9, v9
	v_exp_f32_e32 v10, v10
	v_exp_f32_e32 v11, v11
	v_exp_f32_e32 v4, v4
	v_exp_f32_e32 v5, v5
	v_exp_f32_e32 v6, v6
	v_exp_f32_e32 v7, v7
	v_add_f32_e32 v8, 1.0, v8
	v_add_f32_e32 v9, 1.0, v9
	v_add_f32_e32 v10, 1.0, v10
	v_add_f32_e32 v11, 1.0, v11
	v_add_f32_e32 v4, 1.0, v4
	v_add_f32_e32 v5, 1.0, v5
	v_add_f32_e32 v6, 1.0, v6
	v_add_f32_e32 v7, 1.0, v7
	v_rcp_f32_e32 v8, v8
	v_rcp_f32_e32 v9, v9
	v_rcp_f32_e32 v10, v10
	v_rcp_f32_e32 v11, v11
	v_rcp_f32_e32 v4, v4
	v_rcp_f32_e32 v5, v5
	v_rcp_f32_e32 v6, v6
	v_rcp_f32_e32 v7, v7
	v_mul_f32_e32 v12, v12, v226
	v_mul_f32_e32 v13, v13, v226
	v_mul_f32_e32 v14, v14, v226
	v_mul_f32_e32 v15, v15, v226
	v_mul_f32_e32 v0, v0, v226
	v_mul_f32_e32 v1, v1, v226
	v_mul_f32_e32 v2, v2, v226
	v_mul_f32_e32 v3, v3, v226
	v_mul_f32_e32 v12, v12, v8
	v_mul_f32_e32 v13, v13, v9
	v_mul_f32_e32 v14, v14, v10
	v_mul_f32_e32 v15, v15, v11
	v_mul_f32_e32 v0, v0, v4
	v_mul_f32_e32 v1, v1, v5
	v_mul_f32_e32 v2, v2, v6
	v_mul_f32_e32 v3, v3, v7
	v_cvt_pk_bf16_f32 v8, v12, v13
	v_cvt_pk_bf16_f32 v9, v14, v15
	v_cvt_pk_bf16_f32 v10, v0, v1
	v_cvt_pk_bf16_f32 v11, v2, v3
	global_store_dwordx4 v227, v[8:11], s[10:11]
	s_andn2_b64 vcc, exec, s[8:9]
	s_mov_b64 s[8:9], -1
	s_cbranch_vccnz .LBB0_1283
	s_and_b64 vcc, exec, s[66:67]
	s_cbranch_vccnz .LBB0_1282
	s_barrier
	s_branch .LBB0_1282
